# ph8 epilogue: conv coefficients fetched once per tile with the rstd partials and shared through LDS (ds_read instead of 4 serial global load groups)
# baseline (speedup 1.0000x reference)
.LBB0_984:
	s_lshl_b32 s60, s28, 8
	v_and_b32_e32 v134, 48, v180
	v_and_b32_e32 v135, 64, v180
	v_add_u32_e32 v134, v134, v178
	v_lshl_add_u32 v134, v135, 1, v134
	v_add_u32_e32 v132, s60, v134
	v_ashrrev_i32_e32 v133, 31, v132
	v_lshlrev_b64 v[128:129], 6, v[132:133]
	v_lshl_add_u64 v[136:137], s[16:17], 0, v[128:129]
	global_load_dwordx4 v[128:131], v[136:137], off
	global_load_dwordx4 v[142:145], v[136:137], off offset:16
	global_load_dwordx4 v[138:141], v[136:137], off offset:32
	global_load_dwordx4 v[146:149], v[136:137], off offset:48
	v_lshrrev_b32_e32 v221, 6, v134
	v_and_b32_e32 v222, 31, v134
	v_readfirstlane_b32 s98, v221
	v_and_b32_e32 v223, 32, v134
	v_lshlrev_b32_e32 v222, 4, v222
	v_mul_u32_u24_e32 v223, 0x180, v223
	s_lshl_b32 s99, s8, 9
	v_add3_u32 v222, v222, v223, s99
	s_cmp_eq_u32 s98, 3
	s_mul_i32 s99, s98, 0x6000
	s_cselect_b32 s99, 0, s99
	s_cselect_b32 s100, s26, s24
	s_cselect_b32 s101, s27, s25
	s_add_u32 s100, s100, s99
	s_addc_u32 s101, s101, 0
	global_load_dwordx4 v[224:227], v222, s[100:101]
	s_cmp_lt_u32 s98, 2
	s_mov_b32 s99, 0x1fc00
	s_cselect_b32 s99, 0x23400, s99
	v_lshl_add_u32 v223, v134, 4, s99
	v_lshlrev_b32_e32 v135, 2, v134
	v_add_u32_e32 v135, 0x23000, v135
	s_waitcnt vmcnt(0)
	v_add_f32_e32 v128, v128, v129
	v_add_f32_e32 v130, v130, v131
	v_add_f32_e32 v142, v142, v143
	v_add_f32_e32 v144, v144, v145
	v_add_f32_e32 v138, v138, v139
	v_add_f32_e32 v140, v140, v141
	v_add_f32_e32 v146, v146, v147
	v_add_f32_e32 v148, v148, v149
	v_add_f32_e32 v128, v128, v130
	v_add_f32_e32 v142, v142, v144
	v_add_f32_e32 v138, v138, v140
	v_add_f32_e32 v146, v146, v148
	v_add_f32_e32 v128, v128, v142
	v_add_f32_e32 v138, v138, v146
	v_add_f32_e32 v128, v128, v138
	v_fmamk_f32 v128, v128, 0x3a800000, v214
	v_mul_f32_e32 v129, 0x4b800000, v128
	v_cmp_gt_f32_e32 vcc, s87, v128
	s_nop 1
	v_cndmask_b32_e32 v128, v128, v129, vcc
	v_rsq_f32_e32 v128, v128
	s_nop 0
	v_mul_f32_e32 v129, 0x45800000, v128
	v_cndmask_b32_e32 v128, v128, v129, vcc
	ds_write_b32 v135, v128
	ds_write_b128 v223, v[224:227]
	v_lshlrev_b32_e32 v134, 2, v178
	v_add_u32_e32 v134, 0x23000, v134
	s_waitcnt lgkmcnt(0)
	s_barrier
	v_lshlrev_b32_e32 v220, 2, v180
	v_add_u32_e32 v220, 0x20400, v220
	ds_read2_b32 v[150:151], v134 offset1:16
	ds_read2_b32 v[152:153], v134 offset0:32 offset1:48
	ds_read2_b32 v[154:155], v134 offset0:128 offset1:144
	ds_read2_b32 v[156:157], v134 offset0:160 offset1:176
	s_waitcnt lgkmcnt(0)
	v_pk_mul_f32 v[118:119], v[118:119], v[150:151] op_sel_hi:[1,0]
	v_pk_mul_f32 v[116:117], v[116:117], v[150:151] op_sel_hi:[1,0]
	v_pk_mul_f32 v[26:27], v[26:27], v[150:151] op_sel_hi:[1,0]
	v_pk_mul_f32 v[24:25], v[24:25], v[150:151] op_sel_hi:[1,0]
	v_pk_mul_f32 v[74:75], v[74:75], v[150:151] op_sel_hi:[1,0]
	v_pk_mul_f32 v[72:73], v[72:73], v[150:151] op_sel_hi:[1,0]
	v_pk_mul_f32 v[2:3], v[2:3], v[150:151] op_sel_hi:[1,0]
	v_pk_mul_f32 v[0:1], v[0:1], v[150:151] op_sel_hi:[1,0]
	v_pk_mul_f32 v[126:127], v[126:127], v[150:151] op_sel:[0,1] op_sel_hi:[1,1]
	v_pk_mul_f32 v[124:125], v[124:125], v[150:151] op_sel:[0,1] op_sel_hi:[1,1]
	v_pk_mul_f32 v[34:35], v[34:35], v[150:151] op_sel:[0,1] op_sel_hi:[1,1]
	v_pk_mul_f32 v[32:33], v[32:33], v[150:151] op_sel:[0,1] op_sel_hi:[1,1]
	v_pk_mul_f32 v[90:91], v[90:91], v[150:151] op_sel:[0,1] op_sel_hi:[1,1]
	v_pk_mul_f32 v[88:89], v[88:89], v[150:151] op_sel:[0,1] op_sel_hi:[1,1]
	v_pk_mul_f32 v[6:7], v[6:7], v[150:151] op_sel:[0,1] op_sel_hi:[1,1]
	v_pk_mul_f32 v[4:5], v[4:5], v[150:151] op_sel:[0,1] op_sel_hi:[1,1]
	v_pk_mul_f32 v[130:131], v[122:123], v[152:153] op_sel_hi:[1,0]
	v_pk_mul_f32 v[128:129], v[120:121], v[152:153] op_sel_hi:[1,0]
	v_pk_mul_f32 v[46:47], v[46:47], v[152:153] op_sel_hi:[1,0]
	v_pk_mul_f32 v[44:45], v[44:45], v[152:153] op_sel_hi:[1,0]
	v_pk_mul_f32 v[106:107], v[106:107], v[152:153] op_sel_hi:[1,0]
	v_pk_mul_f32 v[104:105], v[104:105], v[152:153] op_sel_hi:[1,0]
	v_pk_mul_f32 v[14:15], v[14:15], v[152:153] op_sel_hi:[1,0]
	v_pk_mul_f32 v[12:13], v[12:13], v[152:153] op_sel_hi:[1,0]
	v_pk_mul_f32 v[114:115], v[114:115], v[152:153] op_sel:[0,1] op_sel_hi:[1,1]
	v_pk_mul_f32 v[112:113], v[112:113], v[152:153] op_sel:[0,1] op_sel_hi:[1,1]
	v_pk_mul_f32 v[54:55], v[54:55], v[152:153] op_sel:[0,1] op_sel_hi:[1,1]
	v_pk_mul_f32 v[52:53], v[52:53], v[152:153] op_sel:[0,1] op_sel_hi:[1,1]
	v_pk_mul_f32 v[110:111], v[110:111], v[152:153] op_sel:[0,1] op_sel_hi:[1,1]
	v_pk_mul_f32 v[108:109], v[108:109], v[152:153] op_sel:[0,1] op_sel_hi:[1,1]
	v_pk_mul_f32 v[22:23], v[22:23], v[152:153] op_sel:[0,1] op_sel_hi:[1,1]
	v_pk_mul_f32 v[20:21], v[20:21], v[152:153] op_sel:[0,1] op_sel_hi:[1,1]
	v_pk_mul_f32 v[122:123], v[102:103], v[154:155] op_sel_hi:[1,0]
	v_pk_mul_f32 v[120:121], v[100:101], v[154:155] op_sel_hi:[1,0]
	v_pk_mul_f32 v[42:43], v[42:43], v[154:155] op_sel_hi:[1,0]
	v_pk_mul_f32 v[40:41], v[40:41], v[154:155] op_sel_hi:[1,0]
	v_pk_mul_f32 v[98:99], v[98:99], v[154:155] op_sel_hi:[1,0]
	v_pk_mul_f32 v[96:97], v[96:97], v[154:155] op_sel_hi:[1,0]
	v_pk_mul_f32 v[10:11], v[10:11], v[154:155] op_sel_hi:[1,0]
	v_pk_mul_f32 v[8:9], v[8:9], v[154:155] op_sel_hi:[1,0]
	v_pk_mul_f32 v[134:135], v[94:95], v[154:155] op_sel:[0,1] op_sel_hi:[1,1]
	v_pk_mul_f32 v[132:133], v[92:93], v[154:155] op_sel:[0,1] op_sel_hi:[1,1]
	v_pk_mul_f32 v[50:51], v[50:51], v[154:155] op_sel:[0,1] op_sel_hi:[1,1]
	v_pk_mul_f32 v[48:49], v[48:49], v[154:155] op_sel:[0,1] op_sel_hi:[1,1]
	v_pk_mul_f32 v[86:87], v[86:87], v[154:155] op_sel:[0,1] op_sel_hi:[1,1]
	v_pk_mul_f32 v[84:85], v[84:85], v[154:155] op_sel:[0,1] op_sel_hi:[1,1]
	v_pk_mul_f32 v[18:19], v[18:19], v[154:155] op_sel:[0,1] op_sel_hi:[1,1]
	v_pk_mul_f32 v[16:17], v[16:17], v[154:155] op_sel:[0,1] op_sel_hi:[1,1]
	v_pk_mul_f32 v[140:141], v[82:83], v[156:157] op_sel_hi:[1,0]
	v_pk_mul_f32 v[138:139], v[80:81], v[156:157] op_sel_hi:[1,0]
	v_pk_mul_f32 v[58:59], v[58:59], v[156:157] op_sel_hi:[1,0]
	v_pk_mul_f32 v[56:57], v[56:57], v[156:157] op_sel_hi:[1,0]
	v_pk_mul_f32 v[82:83], v[78:79], v[156:157] op_sel_hi:[1,0]
	v_pk_mul_f32 v[80:81], v[76:77], v[156:157] op_sel_hi:[1,0]
	v_pk_mul_f32 v[30:31], v[30:31], v[156:157] op_sel_hi:[1,0]
	v_pk_mul_f32 v[28:29], v[28:29], v[156:157] op_sel_hi:[1,0]
	v_pk_mul_f32 v[94:95], v[70:71], v[156:157] op_sel:[0,1] op_sel_hi:[1,1]
	v_pk_mul_f32 v[92:93], v[68:69], v[156:157] op_sel:[0,1] op_sel_hi:[1,1]
	v_pk_mul_f32 v[62:63], v[62:63], v[156:157] op_sel:[0,1] op_sel_hi:[1,1]
	v_pk_mul_f32 v[60:61], v[60:61], v[156:157] op_sel:[0,1] op_sel_hi:[1,1]
	v_pk_mul_f32 v[66:67], v[66:67], v[156:157] op_sel:[0,1] op_sel_hi:[1,1]
	v_pk_mul_f32 v[64:65], v[64:65], v[156:157] op_sel:[0,1] op_sel_hi:[1,1]
	v_pk_mul_f32 v[38:39], v[38:39], v[156:157] op_sel:[0,1] op_sel_hi:[1,1]
	v_pk_mul_f32 v[36:37], v[36:37], v[156:157] op_sel:[0,1] op_sel_hi:[1,1]
	v_cndmask_b32_e64 v68, 0, 1, s[22:23]
	v_cmp_ne_u32_e64 s[6:7], 1, v68
	s_and_saveexec_b64 s[62:63], s[0:1]
	s_cbranch_execz .LBB0_987
	s_and_b64 vcc, exec, s[6:7]
	ds_write_b128 v175, v[112:115]
	ds_write_b128 v175, v[52:55] offset:16
	ds_write_b128 v175, v[108:111] offset:512
	ds_write_b128 v175, v[20:23] offset:528
	ds_write_b128 v211, v[92:95]
	ds_write_b128 v175, v[60:63] offset:4112
	ds_write_b128 v175, v[64:67] offset:4608
	ds_write_b128 v175, v[36:39] offset:4624
	s_cbranch_vccnz .LBB0_987
	s_ashr_i32 s29, s28, 31
	v_lshl_add_u64 v[68:69], s[28:29], 1, v[176:177]
	v_mov_b64_e32 v[70:71], s[34:35]
	v_mad_u64_u32 v[70:71], s[14:15], v68, s77, v[70:71]
	s_lshl_b32 s14, s8, 8
	v_mad_i32_i24 v71, v69, s77, v71
	s_ashr_i32 s15, s14, 31
	v_lshl_add_u64 v[68:69], s[14:15], 2, v[70:71]
	v_lshlrev_b32_e32 v70, 2, v180
	v_mov_b32_e32 v71, v173
	v_lshl_add_u64 v[68:69], v[68:69], 0, v[70:71]
	global_store_dwordx4 v[68:69], v[92:95], off
	global_store_dwordx4 v[68:69], v[60:63], off offset:16
	global_store_dwordx4 v[68:69], v[64:67], off offset:512
	global_store_dwordx4 v[68:69], v[36:39], off offset:528

.LBB0_989:
	s_or_b64 exec, exec, s[62:63]
	s_lshl_b32 s28, s8, 7
	v_or_b32_e32 v204, s28, v180
	v_ashrrev_i32_e32 v205, 31, v204
	v_lshlrev_b64 v[68:69], 2, v[204:205]
	s_waitcnt lgkmcnt(0)
	s_barrier
	v_lshl_add_u64 v[206:207], s[24:25], 0, v[68:69]
	v_lshl_add_u64 v[70:71], s[36:37], 0, v[68:69]
	v_lshl_add_u64 v[208:209], s[26:27], 0, v[68:69]
	ds_read_b128 v[150:153], v220 offset:12288
	v_lshl_add_u64 v[76:77], s[38:39], 0, v[68:69]
	ds_read_b128 v[146:149], v220 offset:13312
	ds_read_b128 v[142:145], v220 offset:0
	ds_read_b128 v[154:157], v220 offset:1024
	v_cndmask_b32_e64 v68, 0, 1, s[48:49]
	v_mov_b32_e32 v136, 0
	v_cmp_ne_u32_e64 s[8:9], 1, v68
	s_andn2_b64 vcc, exec, s[48:49]
	v_mov_b32_e32 v158, 0
	v_mov_b32_e32 v159, 0
	v_mov_b32_e32 v160, 0
	v_mov_b32_e32 v161, 0
	s_cbranch_vccnz .LBB0_991
	ds_read_b128 v[158:161], v212
.LBB0_991:
	v_mov_b64_e32 v[68:69], v[128:129]
	v_mov_b64_e32 v[70:71], v[130:131]
	s_waitcnt lgkmcnt(0)
	v_pk_fma_f32 v[100:101], v[152:153], v[114:115], v[156:157]
	v_mov_b32_dpp v76, v68 row_ror:1 row_mask:0xf bank_mask:0xf bound_ctrl:1
	v_mov_b32_dpp v77, v69 row_ror:1 row_mask:0xf bank_mask:0xf bound_ctrl:1
	v_mov_b32_dpp v78, v70 row_ror:1 row_mask:0xf bank_mask:0xf bound_ctrl:1
	v_mov_b32_dpp v79, v71 row_ror:1 row_mask:0xf bank_mask:0xf bound_ctrl:1
	v_mov_b32_dpp v76, v112 row_shr:1 row_mask:0xf bank_mask:0xf
	v_mov_b32_dpp v68, v68 row_ror:2 row_mask:0xf bank_mask:0xf bound_ctrl:1
	v_mov_b32_dpp v77, v113 row_shr:1 row_mask:0xf bank_mask:0xf
	v_mov_b32_dpp v69, v69 row_ror:2 row_mask:0xf bank_mask:0xf bound_ctrl:1
	v_mov_b32_dpp v78, v114 row_shr:1 row_mask:0xf bank_mask:0xf
	v_mov_b32_dpp v70, v70 row_ror:2 row_mask:0xf bank_mask:0xf bound_ctrl:1
	v_mov_b32_dpp v79, v115 row_shr:1 row_mask:0xf bank_mask:0xf
	v_mov_b32_dpp v71, v71 row_ror:2 row_mask:0xf bank_mask:0xf bound_ctrl:1
	v_pk_fma_f32 v[102:103], v[150:151], v[112:113], v[154:155]
	v_mov_b32_dpp v68, v112 row_shr:2 row_mask:0xf bank_mask:0xf
	v_mov_b32_dpp v69, v113 row_shr:2 row_mask:0xf bank_mask:0xf
	v_mov_b32_dpp v70, v114 row_shr:2 row_mask:0xf bank_mask:0xf
	v_mov_b32_dpp v71, v115 row_shr:2 row_mask:0xf bank_mask:0xf
	v_pk_fma_f32 v[76:77], v[146:147], v[76:77], v[102:103]
	v_pk_fma_f32 v[78:79], v[148:149], v[78:79], v[100:101]
	v_pk_fma_f32 v[76:77], v[142:143], v[68:69], v[76:77]
	v_pk_fma_f32 v[78:79], v[144:145], v[70:71], v[78:79]
	s_nop 0
	v_mov_b64_e32 v[68:69], v[124:125]
	v_mov_b64_e32 v[70:71], v[126:127]
	s_nop 0
	v_pk_fma_f32 v[112:113], v[152:153], v[130:131], v[156:157]
	v_mov_b32_dpp v100, v68 row_ror:1 row_mask:0xf bank_mask:0xf bound_ctrl:1
	v_mov_b32_dpp v101, v69 row_ror:1 row_mask:0xf bank_mask:0xf bound_ctrl:1
	v_mov_b32_dpp v102, v70 row_ror:1 row_mask:0xf bank_mask:0xf bound_ctrl:1
	v_mov_b32_dpp v103, v71 row_ror:1 row_mask:0xf bank_mask:0xf bound_ctrl:1
	v_mov_b32_dpp v100, v128 row_shr:1 row_mask:0xf bank_mask:0xf
	v_mov_b32_dpp v68, v68 row_ror:2 row_mask:0xf bank_mask:0xf bound_ctrl:1
	v_mov_b32_dpp v101, v129 row_shr:1 row_mask:0xf bank_mask:0xf
	v_mov_b32_dpp v69, v69 row_ror:2 row_mask:0xf bank_mask:0xf bound_ctrl:1
	v_mov_b32_dpp v102, v130 row_shr:1 row_mask:0xf bank_mask:0xf
	v_mov_b32_dpp v70, v70 row_ror:2 row_mask:0xf bank_mask:0xf bound_ctrl:1
	v_mov_b32_dpp v103, v131 row_shr:1 row_mask:0xf bank_mask:0xf
	v_mov_b32_dpp v71, v71 row_ror:2 row_mask:0xf bank_mask:0xf bound_ctrl:1
	v_pk_fma_f32 v[114:115], v[150:151], v[128:129], v[154:155]
	v_mov_b32_dpp v68, v128 row_shr:2 row_mask:0xf bank_mask:0xf
	v_mov_b32_dpp v69, v129 row_shr:2 row_mask:0xf bank_mask:0xf
	v_mov_b32_dpp v70, v130 row_shr:2 row_mask:0xf bank_mask:0xf
	v_mov_b32_dpp v71, v131 row_shr:2 row_mask:0xf bank_mask:0xf
	v_pk_fma_f32 v[100:101], v[146:147], v[100:101], v[114:115]
	v_pk_fma_f32 v[102:103], v[148:149], v[102:103], v[112:113]
	v_pk_fma_f32 v[100:101], v[142:143], v[68:69], v[100:101]
	v_pk_fma_f32 v[102:103], v[144:145], v[70:71], v[102:103]
	s_nop 0
	v_mov_b64_e32 v[68:69], v[116:117]
	v_mov_b64_e32 v[70:71], v[118:119]
	s_nop 1
	v_mov_b32_dpp v112, v68 row_ror:1 row_mask:0xf bank_mask:0xf bound_ctrl:1
	v_mov_b32_dpp v68, v68 row_ror:2 row_mask:0xf bank_mask:0xf bound_ctrl:1
	v_mov_b32_dpp v113, v69 row_ror:1 row_mask:0xf bank_mask:0xf bound_ctrl:1
	v_mov_b32_dpp v69, v69 row_ror:2 row_mask:0xf bank_mask:0xf bound_ctrl:1
	v_mov_b32_dpp v114, v70 row_ror:1 row_mask:0xf bank_mask:0xf bound_ctrl:1
	v_mov_b32_dpp v70, v70 row_ror:2 row_mask:0xf bank_mask:0xf bound_ctrl:1
	v_mov_b32_dpp v115, v71 row_ror:1 row_mask:0xf bank_mask:0xf bound_ctrl:1
	v_mov_b32_dpp v71, v71 row_ror:2 row_mask:0xf bank_mask:0xf bound_ctrl:1
	v_mov_b32_dpp v112, v124 row_shr:1 row_mask:0xf bank_mask:0xf
	v_mov_b32_dpp v68, v124 row_shr:2 row_mask:0xf bank_mask:0xf
	v_mov_b32_dpp v113, v125 row_shr:1 row_mask:0xf bank_mask:0xf
	v_mov_b32_dpp v69, v125 row_shr:2 row_mask:0xf bank_mask:0xf
	v_mov_b32_dpp v114, v126 row_shr:1 row_mask:0xf bank_mask:0xf
	v_mov_b32_dpp v70, v126 row_shr:2 row_mask:0xf bank_mask:0xf
	v_mov_b32_dpp v115, v127 row_shr:1 row_mask:0xf bank_mask:0xf
	v_mov_b32_dpp v71, v127 row_shr:2 row_mask:0xf bank_mask:0xf
	v_pk_fma_f32 v[126:127], v[152:153], v[126:127], v[156:157]
	v_pk_fma_f32 v[124:125], v[150:151], v[124:125], v[154:155]
	v_pk_fma_f32 v[114:115], v[148:149], v[114:115], v[126:127]
	v_pk_fma_f32 v[112:113], v[146:147], v[112:113], v[124:125]
	v_pk_fma_f32 v[70:71], v[144:145], v[70:71], v[114:115]
	v_pk_fma_f32 v[68:69], v[142:143], v[68:69], v[112:113]
	s_nop 0
	s_waitcnt lgkmcnt(0)
	s_nop 1
	v_mov_b32_dpp v112, v158 row_ror:1 row_mask:0xf bank_mask:0xf bound_ctrl:1
	v_mov_b32_dpp v114, v158 row_ror:2 row_mask:0xf bank_mask:0xf bound_ctrl:1
	v_mov_b32_dpp v113, v159 row_ror:1 row_mask:0xf bank_mask:0xf bound_ctrl:1
	v_mov_b32_dpp v115, v159 row_ror:2 row_mask:0xf bank_mask:0xf bound_ctrl:1
	v_mov_b32_dpp v124, v160 row_ror:1 row_mask:0xf bank_mask:0xf bound_ctrl:1
	v_mov_b32_dpp v126, v160 row_ror:2 row_mask:0xf bank_mask:0xf bound_ctrl:1
	v_mov_b32_dpp v125, v161 row_ror:1 row_mask:0xf bank_mask:0xf bound_ctrl:1
	v_mov_b32_dpp v127, v161 row_ror:2 row_mask:0xf bank_mask:0xf bound_ctrl:1
	v_mov_b32_dpp v112, v116 row_shr:1 row_mask:0xf bank_mask:0xf
	v_mov_b32_dpp v114, v116 row_shr:2 row_mask:0xf bank_mask:0xf
	v_mov_b32_dpp v113, v117 row_shr:1 row_mask:0xf bank_mask:0xf
	v_mov_b32_dpp v115, v117 row_shr:2 row_mask:0xf bank_mask:0xf
	v_mov_b32_dpp v124, v118 row_shr:1 row_mask:0xf bank_mask:0xf
	v_mov_b32_dpp v126, v118 row_shr:2 row_mask:0xf bank_mask:0xf
	v_mov_b32_dpp v125, v119 row_shr:1 row_mask:0xf bank_mask:0xf
	v_mov_b32_dpp v127, v119 row_shr:2 row_mask:0xf bank_mask:0xf
	v_pk_fma_f32 v[118:119], v[152:153], v[118:119], v[156:157]
	v_pk_fma_f32 v[116:117], v[150:151], v[116:117], v[154:155]
	s_nop 0
	v_pk_fma_f32 v[112:113], v[146:147], v[112:113], v[116:117]
	v_pk_fma_f32 v[116:117], v[148:149], v[124:125], v[118:119]
	v_pk_fma_f32 v[124:125], v[142:143], v[114:115], v[112:113]
	v_pk_fma_f32 v[126:127], v[144:145], v[126:127], v[116:117]
	s_nop 0
	v_mov_b64_e32 v[112:113], v[138:139]
	v_mov_b64_e32 v[114:115], v[140:141]
	ds_read_b128 v[128:131], v212 offset:4096
	s_nop 1
	v_mov_b32_dpp v116, v112 row_ror:1 row_mask:0xf bank_mask:0xf bound_ctrl:1
	v_mov_b32_dpp v112, v112 row_ror:2 row_mask:0xf bank_mask:0xf bound_ctrl:1
	v_mov_b32_dpp v117, v113 row_ror:1 row_mask:0xf bank_mask:0xf bound_ctrl:1
	v_mov_b32_dpp v113, v113 row_ror:2 row_mask:0xf bank_mask:0xf bound_ctrl:1
	v_mov_b32_dpp v118, v114 row_ror:1 row_mask:0xf bank_mask:0xf bound_ctrl:1
	v_mov_b32_dpp v114, v114 row_ror:2 row_mask:0xf bank_mask:0xf bound_ctrl:1
	v_mov_b32_dpp v119, v115 row_ror:1 row_mask:0xf bank_mask:0xf bound_ctrl:1
	v_mov_b32_dpp v115, v115 row_ror:2 row_mask:0xf bank_mask:0xf bound_ctrl:1
	v_mov_b32_dpp v116, v92 row_shr:1 row_mask:0xf bank_mask:0xf
	v_mov_b32_dpp v112, v92 row_shr:2 row_mask:0xf bank_mask:0xf
	v_mov_b32_dpp v117, v93 row_shr:1 row_mask:0xf bank_mask:0xf
	v_mov_b32_dpp v113, v93 row_shr:2 row_mask:0xf bank_mask:0xf
	v_mov_b32_dpp v118, v94 row_shr:1 row_mask:0xf bank_mask:0xf
	v_mov_b32_dpp v114, v94 row_shr:2 row_mask:0xf bank_mask:0xf
	v_mov_b32_dpp v119, v95 row_shr:1 row_mask:0xf bank_mask:0xf
	v_mov_b32_dpp v115, v95 row_shr:2 row_mask:0xf bank_mask:0xf
	v_pk_fma_f32 v[94:95], v[152:153], v[94:95], v[156:157]
	v_pk_fma_f32 v[92:93], v[150:151], v[92:93], v[154:155]
	v_pk_fma_f32 v[94:95], v[148:149], v[118:119], v[94:95]
	v_pk_fma_f32 v[92:93], v[146:147], v[116:117], v[92:93]
	v_pk_fma_f32 v[94:95], v[144:145], v[114:115], v[94:95]
	v_pk_fma_f32 v[92:93], v[142:143], v[112:113], v[92:93]
	s_nop 0
	v_mov_b64_e32 v[112:113], v[132:133]
	v_mov_b64_e32 v[114:115], v[134:135]
	s_nop 1
	v_mov_b32_dpp v116, v112 row_ror:1 row_mask:0xf bank_mask:0xf bound_ctrl:1
	v_mov_b32_dpp v112, v112 row_ror:2 row_mask:0xf bank_mask:0xf bound_ctrl:1
	v_mov_b32_dpp v117, v113 row_ror:1 row_mask:0xf bank_mask:0xf bound_ctrl:1
	v_mov_b32_dpp v113, v113 row_ror:2 row_mask:0xf bank_mask:0xf bound_ctrl:1
	v_mov_b32_dpp v118, v114 row_ror:1 row_mask:0xf bank_mask:0xf bound_ctrl:1
	v_mov_b32_dpp v114, v114 row_ror:2 row_mask:0xf bank_mask:0xf bound_ctrl:1
	v_mov_b32_dpp v119, v115 row_ror:1 row_mask:0xf bank_mask:0xf bound_ctrl:1
	v_mov_b32_dpp v115, v115 row_ror:2 row_mask:0xf bank_mask:0xf bound_ctrl:1
	v_mov_b32_dpp v116, v138 row_shr:1 row_mask:0xf bank_mask:0xf
	v_mov_b32_dpp v112, v138 row_shr:2 row_mask:0xf bank_mask:0xf
	v_mov_b32_dpp v117, v139 row_shr:1 row_mask:0xf bank_mask:0xf
	v_mov_b32_dpp v113, v139 row_shr:2 row_mask:0xf bank_mask:0xf
	v_mov_b32_dpp v118, v140 row_shr:1 row_mask:0xf bank_mask:0xf
	v_mov_b32_dpp v114, v140 row_shr:2 row_mask:0xf bank_mask:0xf
	v_mov_b32_dpp v119, v141 row_shr:1 row_mask:0xf bank_mask:0xf
	v_mov_b32_dpp v115, v141 row_shr:2 row_mask:0xf bank_mask:0xf
	v_pk_fma_f32 v[140:141], v[152:153], v[140:141], v[156:157]
	v_pk_fma_f32 v[138:139], v[150:151], v[138:139], v[154:155]
	v_pk_fma_f32 v[118:119], v[148:149], v[118:119], v[140:141]
	v_pk_fma_f32 v[116:117], v[146:147], v[116:117], v[138:139]
	v_pk_fma_f32 v[114:115], v[144:145], v[114:115], v[118:119]
	v_pk_fma_f32 v[112:113], v[142:143], v[112:113], v[116:117]
	s_nop 0
	v_mov_b64_e32 v[116:117], v[120:121]
	v_mov_b64_e32 v[118:119], v[122:123]
	s_nop 1
	v_mov_b32_dpp v138, v116 row_ror:1 row_mask:0xf bank_mask:0xf bound_ctrl:1
	v_mov_b32_dpp v116, v116 row_ror:2 row_mask:0xf bank_mask:0xf bound_ctrl:1
	v_mov_b32_dpp v139, v117 row_ror:1 row_mask:0xf bank_mask:0xf bound_ctrl:1
	v_mov_b32_dpp v117, v117 row_ror:2 row_mask:0xf bank_mask:0xf bound_ctrl:1
	v_mov_b32_dpp v140, v118 row_ror:1 row_mask:0xf bank_mask:0xf bound_ctrl:1
	v_mov_b32_dpp v118, v118 row_ror:2 row_mask:0xf bank_mask:0xf bound_ctrl:1
	v_mov_b32_dpp v141, v119 row_ror:1 row_mask:0xf bank_mask:0xf bound_ctrl:1
	v_mov_b32_dpp v119, v119 row_ror:2 row_mask:0xf bank_mask:0xf bound_ctrl:1
	v_mov_b32_dpp v138, v132 row_shr:1 row_mask:0xf bank_mask:0xf
	v_mov_b32_dpp v116, v132 row_shr:2 row_mask:0xf bank_mask:0xf
	v_mov_b32_dpp v139, v133 row_shr:1 row_mask:0xf bank_mask:0xf
	v_mov_b32_dpp v117, v133 row_shr:2 row_mask:0xf bank_mask:0xf
	v_mov_b32_dpp v140, v134 row_shr:1 row_mask:0xf bank_mask:0xf
	v_mov_b32_dpp v118, v134 row_shr:2 row_mask:0xf bank_mask:0xf
	v_mov_b32_dpp v141, v135 row_shr:1 row_mask:0xf bank_mask:0xf
	v_mov_b32_dpp v119, v135 row_shr:2 row_mask:0xf bank_mask:0xf
	v_pk_fma_f32 v[134:135], v[152:153], v[134:135], v[156:157]
	v_pk_fma_f32 v[132:133], v[150:151], v[132:133], v[154:155]
	v_pk_fma_f32 v[134:135], v[148:149], v[140:141], v[134:135]
	v_pk_fma_f32 v[132:133], v[146:147], v[138:139], v[132:133]
	v_pk_fma_f32 v[118:119], v[144:145], v[118:119], v[134:135]
	v_pk_fma_f32 v[116:117], v[142:143], v[116:117], v[132:133]
	s_nop 0
	s_waitcnt lgkmcnt(0)
	s_nop 1
	v_mov_b32_dpp v132, v128 row_ror:1 row_mask:0xf bank_mask:0xf bound_ctrl:1
	v_mov_b32_dpp v128, v128 row_ror:2 row_mask:0xf bank_mask:0xf bound_ctrl:1
	v_mov_b32_dpp v133, v129 row_ror:1 row_mask:0xf bank_mask:0xf bound_ctrl:1
	v_mov_b32_dpp v129, v129 row_ror:2 row_mask:0xf bank_mask:0xf bound_ctrl:1
	v_mov_b32_dpp v134, v130 row_ror:1 row_mask:0xf bank_mask:0xf bound_ctrl:1
	v_mov_b32_dpp v130, v130 row_ror:2 row_mask:0xf bank_mask:0xf bound_ctrl:1
	v_mov_b32_dpp v135, v131 row_ror:1 row_mask:0xf bank_mask:0xf bound_ctrl:1
	v_mov_b32_dpp v131, v131 row_ror:2 row_mask:0xf bank_mask:0xf bound_ctrl:1
	v_mov_b32_dpp v132, v120 row_shr:1 row_mask:0xf bank_mask:0xf
	v_mov_b32_dpp v128, v120 row_shr:2 row_mask:0xf bank_mask:0xf
	v_mov_b32_dpp v133, v121 row_shr:1 row_mask:0xf bank_mask:0xf
	v_mov_b32_dpp v129, v121 row_shr:2 row_mask:0xf bank_mask:0xf
	v_mov_b32_dpp v134, v122 row_shr:1 row_mask:0xf bank_mask:0xf
	v_mov_b32_dpp v130, v122 row_shr:2 row_mask:0xf bank_mask:0xf
	v_mov_b32_dpp v135, v123 row_shr:1 row_mask:0xf bank_mask:0xf
	v_mov_b32_dpp v131, v123 row_shr:2 row_mask:0xf bank_mask:0xf
	v_pk_fma_f32 v[122:123], v[152:153], v[122:123], v[156:157]
	v_pk_fma_f32 v[120:121], v[150:151], v[120:121], v[154:155]
	v_pk_fma_f32 v[122:123], v[148:149], v[134:135], v[122:123]
	v_pk_fma_f32 v[120:121], v[146:147], v[132:133], v[120:121]
	v_pk_fma_f32 v[122:123], v[144:145], v[130:131], v[122:123]
	v_pk_fma_f32 v[120:121], v[142:143], v[128:129], v[120:121]
	s_nop 0
	v_add_u32_e32 v128, 0xc00, v204
	v_ashrrev_i32_e32 v129, 31, v128
	v_lshlrev_b64 v[128:129], 2, v[128:129]
	v_lshl_add_u64 v[130:131], s[24:25], 0, v[128:129]
	v_lshl_add_u64 v[132:133], s[36:37], 0, v[128:129]
	ds_read_b128 v[144:147], v220 offset:12800
	ds_read_b128 v[140:143], v220 offset:13824
	v_lshl_add_u64 v[130:131], s[38:39], 0, v[128:129]
	v_lshl_add_u64 v[128:129], s[26:27], 0, v[128:129]
	ds_read_b128 v[132:135], v220 offset:512
	ds_read_b128 v[148:151], v220 offset:1536
	s_and_b64 vcc, exec, s[8:9]
	v_mov_b32_e32 v137, 0
	v_mov_b32_e32 v138, 0
	v_mov_b32_e32 v139, 0
	s_cbranch_vccnz .LBB0_993
	ds_read_b128 v[136:139], v212 offset:512
.LBB0_993:
	v_mov_b64_e32 v[130:131], v[106:107]
	v_mov_b64_e32 v[128:129], v[104:105]
	s_nop 1
	v_mov_b32_dpp v152, v128 row_ror:1 row_mask:0xf bank_mask:0xf bound_ctrl:1
	v_mov_b32_dpp v128, v128 row_ror:2 row_mask:0xf bank_mask:0xf bound_ctrl:1
	v_mov_b32_dpp v153, v129 row_ror:1 row_mask:0xf bank_mask:0xf bound_ctrl:1
	v_mov_b32_dpp v129, v129 row_ror:2 row_mask:0xf bank_mask:0xf bound_ctrl:1
	v_mov_b32_dpp v154, v130 row_ror:1 row_mask:0xf bank_mask:0xf bound_ctrl:1
	v_mov_b32_dpp v130, v130 row_ror:2 row_mask:0xf bank_mask:0xf bound_ctrl:1
	v_mov_b32_dpp v155, v131 row_ror:1 row_mask:0xf bank_mask:0xf bound_ctrl:1
	v_mov_b32_dpp v131, v131 row_ror:2 row_mask:0xf bank_mask:0xf bound_ctrl:1
	v_mov_b32_dpp v152, v108 row_shr:1 row_mask:0xf bank_mask:0xf
	v_mov_b32_dpp v128, v108 row_shr:2 row_mask:0xf bank_mask:0xf
	v_mov_b32_dpp v153, v109 row_shr:1 row_mask:0xf bank_mask:0xf
	v_mov_b32_dpp v129, v109 row_shr:2 row_mask:0xf bank_mask:0xf
	v_mov_b32_dpp v154, v110 row_shr:1 row_mask:0xf bank_mask:0xf
	v_mov_b32_dpp v130, v110 row_shr:2 row_mask:0xf bank_mask:0xf
	v_mov_b32_dpp v155, v111 row_shr:1 row_mask:0xf bank_mask:0xf
	v_mov_b32_dpp v131, v111 row_shr:2 row_mask:0xf bank_mask:0xf
	s_waitcnt lgkmcnt(0)
	v_pk_fma_f32 v[110:111], v[146:147], v[110:111], v[150:151]
	v_pk_fma_f32 v[108:109], v[144:145], v[108:109], v[148:149]
	v_pk_fma_f32 v[110:111], v[142:143], v[154:155], v[110:111]
	v_pk_fma_f32 v[108:109], v[140:141], v[152:153], v[108:109]
	v_pk_fma_f32 v[110:111], v[134:135], v[130:131], v[110:111]
	v_pk_fma_f32 v[108:109], v[132:133], v[128:129], v[108:109]
	s_nop 0
	v_mov_b64_e32 v[130:131], v[90:91]
	v_mov_b64_e32 v[128:129], v[88:89]
	s_nop 1
	v_mov_b32_dpp v152, v128 row_ror:1 row_mask:0xf bank_mask:0xf bound_ctrl:1
	v_mov_b32_dpp v128, v128 row_ror:2 row_mask:0xf bank_mask:0xf bound_ctrl:1
	v_mov_b32_dpp v153, v129 row_ror:1 row_mask:0xf bank_mask:0xf bound_ctrl:1
	v_mov_b32_dpp v129, v129 row_ror:2 row_mask:0xf bank_mask:0xf bound_ctrl:1
	v_mov_b32_dpp v154, v130 row_ror:1 row_mask:0xf bank_mask:0xf bound_ctrl:1
	v_mov_b32_dpp v130, v130 row_ror:2 row_mask:0xf bank_mask:0xf bound_ctrl:1
	v_mov_b32_dpp v155, v131 row_ror:1 row_mask:0xf bank_mask:0xf bound_ctrl:1
	v_mov_b32_dpp v131, v131 row_ror:2 row_mask:0xf bank_mask:0xf bound_ctrl:1
	v_mov_b32_dpp v152, v104 row_shr:1 row_mask:0xf bank_mask:0xf
	v_mov_b32_dpp v128, v104 row_shr:2 row_mask:0xf bank_mask:0xf
	v_mov_b32_dpp v153, v105 row_shr:1 row_mask:0xf bank_mask:0xf
	v_mov_b32_dpp v129, v105 row_shr:2 row_mask:0xf bank_mask:0xf
	v_mov_b32_dpp v154, v106 row_shr:1 row_mask:0xf bank_mask:0xf
	v_mov_b32_dpp v130, v106 row_shr:2 row_mask:0xf bank_mask:0xf
	v_mov_b32_dpp v155, v107 row_shr:1 row_mask:0xf bank_mask:0xf
	v_mov_b32_dpp v131, v107 row_shr:2 row_mask:0xf bank_mask:0xf
	v_pk_fma_f32 v[106:107], v[146:147], v[106:107], v[150:151]
	v_pk_fma_f32 v[104:105], v[144:145], v[104:105], v[148:149]
	v_pk_fma_f32 v[106:107], v[142:143], v[154:155], v[106:107]
	v_pk_fma_f32 v[104:105], v[140:141], v[152:153], v[104:105]
	v_pk_fma_f32 v[130:131], v[134:135], v[130:131], v[106:107]
	v_pk_fma_f32 v[128:129], v[132:133], v[128:129], v[104:105]
	s_nop 0
	v_mov_b64_e32 v[106:107], v[74:75]
	v_mov_b64_e32 v[104:105], v[72:73]
	s_nop 1
	v_mov_b32_dpp v152, v104 row_ror:1 row_mask:0xf bank_mask:0xf bound_ctrl:1
	v_mov_b32_dpp v104, v104 row_ror:2 row_mask:0xf bank_mask:0xf bound_ctrl:1
	v_mov_b32_dpp v153, v105 row_ror:1 row_mask:0xf bank_mask:0xf bound_ctrl:1
	v_mov_b32_dpp v105, v105 row_ror:2 row_mask:0xf bank_mask:0xf bound_ctrl:1
	v_mov_b32_dpp v154, v106 row_ror:1 row_mask:0xf bank_mask:0xf bound_ctrl:1
	v_mov_b32_dpp v106, v106 row_ror:2 row_mask:0xf bank_mask:0xf bound_ctrl:1
	v_mov_b32_dpp v155, v107 row_ror:1 row_mask:0xf bank_mask:0xf bound_ctrl:1
	v_mov_b32_dpp v107, v107 row_ror:2 row_mask:0xf bank_mask:0xf bound_ctrl:1
	v_mov_b32_dpp v152, v88 row_shr:1 row_mask:0xf bank_mask:0xf
	v_mov_b32_dpp v104, v88 row_shr:2 row_mask:0xf bank_mask:0xf
	v_mov_b32_dpp v153, v89 row_shr:1 row_mask:0xf bank_mask:0xf
	v_mov_b32_dpp v105, v89 row_shr:2 row_mask:0xf bank_mask:0xf
	v_mov_b32_dpp v154, v90 row_shr:1 row_mask:0xf bank_mask:0xf
	v_mov_b32_dpp v106, v90 row_shr:2 row_mask:0xf bank_mask:0xf
	v_mov_b32_dpp v155, v91 row_shr:1 row_mask:0xf bank_mask:0xf
	v_mov_b32_dpp v107, v91 row_shr:2 row_mask:0xf bank_mask:0xf
	v_pk_fma_f32 v[90:91], v[146:147], v[90:91], v[150:151]
	v_pk_fma_f32 v[88:89], v[144:145], v[88:89], v[148:149]
	v_pk_fma_f32 v[90:91], v[142:143], v[154:155], v[90:91]
	v_pk_fma_f32 v[88:89], v[140:141], v[152:153], v[88:89]
	v_pk_fma_f32 v[154:155], v[134:135], v[106:107], v[90:91]
	v_pk_fma_f32 v[152:153], v[132:133], v[104:105], v[88:89]
	s_nop 0
	s_waitcnt lgkmcnt(0)
	s_nop 1
	v_mov_b32_dpp v88, v136 row_ror:1 row_mask:0xf bank_mask:0xf bound_ctrl:1
	v_mov_b32_dpp v90, v136 row_ror:2 row_mask:0xf bank_mask:0xf bound_ctrl:1
	v_mov_b32_dpp v89, v137 row_ror:1 row_mask:0xf bank_mask:0xf bound_ctrl:1
	v_mov_b32_dpp v91, v137 row_ror:2 row_mask:0xf bank_mask:0xf bound_ctrl:1
	v_mov_b32_dpp v104, v138 row_ror:1 row_mask:0xf bank_mask:0xf bound_ctrl:1
	v_mov_b32_dpp v106, v138 row_ror:2 row_mask:0xf bank_mask:0xf bound_ctrl:1
	v_mov_b32_dpp v105, v139 row_ror:1 row_mask:0xf bank_mask:0xf bound_ctrl:1
	v_mov_b32_dpp v107, v139 row_ror:2 row_mask:0xf bank_mask:0xf bound_ctrl:1
	v_mov_b32_dpp v88, v72 row_shr:1 row_mask:0xf bank_mask:0xf
	v_mov_b32_dpp v90, v72 row_shr:2 row_mask:0xf bank_mask:0xf
	v_mov_b32_dpp v89, v73 row_shr:1 row_mask:0xf bank_mask:0xf
	v_mov_b32_dpp v91, v73 row_shr:2 row_mask:0xf bank_mask:0xf
	v_mov_b32_dpp v104, v74 row_shr:1 row_mask:0xf bank_mask:0xf
	v_mov_b32_dpp v106, v74 row_shr:2 row_mask:0xf bank_mask:0xf
	v_mov_b32_dpp v105, v75 row_shr:1 row_mask:0xf bank_mask:0xf
	v_mov_b32_dpp v107, v75 row_shr:2 row_mask:0xf bank_mask:0xf
	v_pk_fma_f32 v[74:75], v[146:147], v[74:75], v[150:151]
	v_pk_fma_f32 v[72:73], v[144:145], v[72:73], v[148:149]
	v_pk_fma_f32 v[74:75], v[142:143], v[104:105], v[74:75]
	v_pk_fma_f32 v[72:73], v[140:141], v[88:89], v[72:73]
	v_pk_fma_f32 v[74:75], v[134:135], v[106:107], v[74:75]
	v_pk_fma_f32 v[72:73], v[132:133], v[90:91], v[72:73]
	s_nop 0
	v_mov_b64_e32 v[90:91], v[82:83]
	v_mov_b64_e32 v[88:89], v[80:81]
	ds_read_b128 v[136:139], v212 offset:4608
	s_nop 1
	v_mov_b32_dpp v104, v88 row_ror:1 row_mask:0xf bank_mask:0xf bound_ctrl:1
	v_mov_b32_dpp v88, v88 row_ror:2 row_mask:0xf bank_mask:0xf bound_ctrl:1
	v_mov_b32_dpp v105, v89 row_ror:1 row_mask:0xf bank_mask:0xf bound_ctrl:1
	v_mov_b32_dpp v89, v89 row_ror:2 row_mask:0xf bank_mask:0xf bound_ctrl:1
	v_mov_b32_dpp v106, v90 row_ror:1 row_mask:0xf bank_mask:0xf bound_ctrl:1
	v_mov_b32_dpp v90, v90 row_ror:2 row_mask:0xf bank_mask:0xf bound_ctrl:1
	v_mov_b32_dpp v107, v91 row_ror:1 row_mask:0xf bank_mask:0xf bound_ctrl:1
	v_mov_b32_dpp v91, v91 row_ror:2 row_mask:0xf bank_mask:0xf bound_ctrl:1
	v_mov_b32_dpp v104, v64 row_shr:1 row_mask:0xf bank_mask:0xf
	v_mov_b32_dpp v88, v64 row_shr:2 row_mask:0xf bank_mask:0xf
	v_mov_b32_dpp v105, v65 row_shr:1 row_mask:0xf bank_mask:0xf
	v_mov_b32_dpp v89, v65 row_shr:2 row_mask:0xf bank_mask:0xf
	v_mov_b32_dpp v106, v66 row_shr:1 row_mask:0xf bank_mask:0xf
	v_mov_b32_dpp v90, v66 row_shr:2 row_mask:0xf bank_mask:0xf
	v_mov_b32_dpp v107, v67 row_shr:1 row_mask:0xf bank_mask:0xf
	v_mov_b32_dpp v91, v67 row_shr:2 row_mask:0xf bank_mask:0xf
	v_pk_fma_f32 v[66:67], v[146:147], v[66:67], v[150:151]
	v_pk_fma_f32 v[64:65], v[144:145], v[64:65], v[148:149]
	v_pk_fma_f32 v[66:67], v[142:143], v[106:107], v[66:67]
	v_pk_fma_f32 v[64:65], v[140:141], v[104:105], v[64:65]
	v_pk_fma_f32 v[106:107], v[134:135], v[90:91], v[66:67]
	v_pk_fma_f32 v[104:105], v[132:133], v[88:89], v[64:65]
	s_nop 0
	v_mov_b64_e32 v[64:65], v[84:85]
	v_mov_b64_e32 v[66:67], v[86:87]
	s_nop 1
	v_mov_b32_dpp v88, v64 row_ror:1 row_mask:0xf bank_mask:0xf bound_ctrl:1
	v_mov_b32_dpp v64, v64 row_ror:2 row_mask:0xf bank_mask:0xf bound_ctrl:1
	v_mov_b32_dpp v89, v65 row_ror:1 row_mask:0xf bank_mask:0xf bound_ctrl:1
	v_mov_b32_dpp v65, v65 row_ror:2 row_mask:0xf bank_mask:0xf bound_ctrl:1
	v_mov_b32_dpp v90, v66 row_ror:1 row_mask:0xf bank_mask:0xf bound_ctrl:1
	v_mov_b32_dpp v66, v66 row_ror:2 row_mask:0xf bank_mask:0xf bound_ctrl:1
	v_mov_b32_dpp v91, v67 row_ror:1 row_mask:0xf bank_mask:0xf bound_ctrl:1
	v_mov_b32_dpp v67, v67 row_ror:2 row_mask:0xf bank_mask:0xf bound_ctrl:1
	v_mov_b32_dpp v88, v80 row_shr:1 row_mask:0xf bank_mask:0xf
	v_mov_b32_dpp v64, v80 row_shr:2 row_mask:0xf bank_mask:0xf
	v_mov_b32_dpp v89, v81 row_shr:1 row_mask:0xf bank_mask:0xf
	v_mov_b32_dpp v65, v81 row_shr:2 row_mask:0xf bank_mask:0xf
	v_mov_b32_dpp v90, v82 row_shr:1 row_mask:0xf bank_mask:0xf
	v_mov_b32_dpp v66, v82 row_shr:2 row_mask:0xf bank_mask:0xf
	v_mov_b32_dpp v91, v83 row_shr:1 row_mask:0xf bank_mask:0xf
	v_mov_b32_dpp v67, v83 row_shr:2 row_mask:0xf bank_mask:0xf
	v_pk_fma_f32 v[82:83], v[146:147], v[82:83], v[150:151]
	v_pk_fma_f32 v[80:81], v[144:145], v[80:81], v[148:149]
	v_pk_fma_f32 v[82:83], v[142:143], v[90:91], v[82:83]
	v_pk_fma_f32 v[80:81], v[140:141], v[88:89], v[80:81]
	v_pk_fma_f32 v[90:91], v[134:135], v[66:67], v[82:83]
	v_pk_fma_f32 v[88:89], v[132:133], v[64:65], v[80:81]
	s_nop 0
	v_mov_b64_e32 v[64:65], v[96:97]
	v_mov_b64_e32 v[66:67], v[98:99]
	s_nop 1
	v_mov_b32_dpp v80, v64 row_ror:1 row_mask:0xf bank_mask:0xf bound_ctrl:1
	v_mov_b32_dpp v64, v64 row_ror:2 row_mask:0xf bank_mask:0xf bound_ctrl:1
	v_mov_b32_dpp v81, v65 row_ror:1 row_mask:0xf bank_mask:0xf bound_ctrl:1
	v_mov_b32_dpp v65, v65 row_ror:2 row_mask:0xf bank_mask:0xf bound_ctrl:1
	v_mov_b32_dpp v82, v66 row_ror:1 row_mask:0xf bank_mask:0xf bound_ctrl:1
	v_mov_b32_dpp v66, v66 row_ror:2 row_mask:0xf bank_mask:0xf bound_ctrl:1
	v_mov_b32_dpp v83, v67 row_ror:1 row_mask:0xf bank_mask:0xf bound_ctrl:1
	v_mov_b32_dpp v67, v67 row_ror:2 row_mask:0xf bank_mask:0xf bound_ctrl:1
	v_mov_b32_dpp v80, v84 row_shr:1 row_mask:0xf bank_mask:0xf
	v_mov_b32_dpp v64, v84 row_shr:2 row_mask:0xf bank_mask:0xf
	v_mov_b32_dpp v81, v85 row_shr:1 row_mask:0xf bank_mask:0xf
	v_mov_b32_dpp v65, v85 row_shr:2 row_mask:0xf bank_mask:0xf
	v_mov_b32_dpp v82, v86 row_shr:1 row_mask:0xf bank_mask:0xf
	v_mov_b32_dpp v66, v86 row_shr:2 row_mask:0xf bank_mask:0xf
	v_mov_b32_dpp v83, v87 row_shr:1 row_mask:0xf bank_mask:0xf
	v_mov_b32_dpp v67, v87 row_shr:2 row_mask:0xf bank_mask:0xf
	v_pk_fma_f32 v[86:87], v[146:147], v[86:87], v[150:151]
	v_pk_fma_f32 v[84:85], v[144:145], v[84:85], v[148:149]
	v_pk_fma_f32 v[82:83], v[142:143], v[82:83], v[86:87]
	v_pk_fma_f32 v[80:81], v[140:141], v[80:81], v[84:85]
	v_pk_fma_f32 v[86:87], v[134:135], v[66:67], v[82:83]
	v_pk_fma_f32 v[84:85], v[132:133], v[64:65], v[80:81]
	s_nop 0
	s_waitcnt lgkmcnt(0)
	s_nop 1
	v_mov_b32_dpp v64, v136 row_ror:1 row_mask:0xf bank_mask:0xf bound_ctrl:1
	v_mov_b32_dpp v66, v136 row_ror:2 row_mask:0xf bank_mask:0xf bound_ctrl:1
	v_mov_b32_dpp v65, v137 row_ror:1 row_mask:0xf bank_mask:0xf bound_ctrl:1
	v_mov_b32_dpp v67, v137 row_ror:2 row_mask:0xf bank_mask:0xf bound_ctrl:1
	v_mov_b32_dpp v80, v138 row_ror:1 row_mask:0xf bank_mask:0xf bound_ctrl:1
	v_mov_b32_dpp v82, v138 row_ror:2 row_mask:0xf bank_mask:0xf bound_ctrl:1
	v_mov_b32_dpp v81, v139 row_ror:1 row_mask:0xf bank_mask:0xf bound_ctrl:1
	v_mov_b32_dpp v83, v139 row_ror:2 row_mask:0xf bank_mask:0xf bound_ctrl:1
	v_mov_b32_dpp v64, v96 row_shr:1 row_mask:0xf bank_mask:0xf
	v_mov_b32_dpp v66, v96 row_shr:2 row_mask:0xf bank_mask:0xf
	v_mov_b32_dpp v65, v97 row_shr:1 row_mask:0xf bank_mask:0xf
	v_mov_b32_dpp v67, v97 row_shr:2 row_mask:0xf bank_mask:0xf
	v_mov_b32_dpp v80, v98 row_shr:1 row_mask:0xf bank_mask:0xf
	v_mov_b32_dpp v82, v98 row_shr:2 row_mask:0xf bank_mask:0xf
	v_mov_b32_dpp v81, v99 row_shr:1 row_mask:0xf bank_mask:0xf
	v_mov_b32_dpp v83, v99 row_shr:2 row_mask:0xf bank_mask:0xf
	v_pk_fma_f32 v[98:99], v[146:147], v[98:99], v[150:151]
	v_pk_fma_f32 v[96:97], v[144:145], v[96:97], v[148:149]
	v_pk_fma_f32 v[80:81], v[142:143], v[80:81], v[98:99]
	v_pk_fma_f32 v[64:65], v[140:141], v[64:65], v[96:97]
	v_pk_fma_f32 v[82:83], v[134:135], v[82:83], v[80:81]
	v_pk_fma_f32 v[80:81], v[132:133], v[66:67], v[64:65]
	s_nop 0
	v_mul_f32_e32 v64, v124, v124
	v_mul_f32_e32 v65, v125, v125
	v_mul_f32_e32 v66, v126, v126
	v_mul_f32_e32 v67, v127, v127
	v_fmamk_f32 v64, v64, 0xbdd2d3e2, v215
	v_fmamk_f32 v65, v65, 0xbdd2d3e2, v215
	v_fmamk_f32 v66, v66, 0xbdd2d3e2, v215
	v_fmamk_f32 v67, v67, 0xbdd2d3e2, v215
	v_mul_f32_e32 v64, v124, v64
	v_mul_f32_e32 v65, v125, v65
	v_mul_f32_e32 v66, v126, v66
	v_mul_f32_e32 v67, v127, v67
	v_exp_f32_e32 v64, v64
	v_exp_f32_e32 v65, v65
	v_exp_f32_e32 v66, v66
	v_exp_f32_e32 v67, v67
	v_add_f32_e32 v64, 1.0, v64
	v_add_f32_e32 v65, 1.0, v65
	v_add_f32_e32 v66, 1.0, v66
	v_add_f32_e32 v67, 1.0, v67
	v_rcp_f32_e32 v64, v64
	v_rcp_f32_e32 v65, v65
	v_rcp_f32_e32 v66, v66
	v_rcp_f32_e32 v67, v67
	v_pk_mul_f32 v[64:65], v[124:125], v[64:65]
	s_nop 0
	v_pk_mul_f32 v[64:65], v[64:65], v[72:73]
	v_pk_mul_f32 v[66:67], v[126:127], v[66:67]
	s_nop 0
	v_pk_mul_f32 v[66:67], v[66:67], v[74:75]
	s_nop 0
	v_mul_f32_e32 v72, v68, v68
	v_mul_f32_e32 v73, v69, v69
	v_mul_f32_e32 v74, v70, v70
	v_mul_f32_e32 v75, v71, v71
	v_fmamk_f32 v72, v72, 0xbdd2d3e2, v215
	v_fmamk_f32 v73, v73, 0xbdd2d3e2, v215
	v_fmamk_f32 v74, v74, 0xbdd2d3e2, v215
	v_fmamk_f32 v75, v75, 0xbdd2d3e2, v215
	v_mul_f32_e32 v72, v68, v72
	v_mul_f32_e32 v73, v69, v73
	v_mul_f32_e32 v74, v70, v74
	v_mul_f32_e32 v75, v71, v75
	v_exp_f32_e32 v72, v72
	v_exp_f32_e32 v73, v73
	v_exp_f32_e32 v74, v74
	v_exp_f32_e32 v75, v75
	v_add_f32_e32 v72, 1.0, v72
	v_add_f32_e32 v73, 1.0, v73
	v_add_f32_e32 v74, 1.0, v74
	v_add_f32_e32 v75, 1.0, v75
	v_rcp_f32_e32 v72, v72
	v_rcp_f32_e32 v73, v73
	v_rcp_f32_e32 v74, v74
	v_rcp_f32_e32 v75, v75
	v_pk_mul_f32 v[68:69], v[68:69], v[72:73]
	s_nop 0
	v_pk_mul_f32 v[68:69], v[68:69], v[152:153]
	v_pk_mul_f32 v[70:71], v[70:71], v[74:75]
	s_nop 0
	v_pk_mul_f32 v[70:71], v[70:71], v[154:155]
	s_nop 0
	v_mul_f32_e32 v72, v100, v100
	v_mul_f32_e32 v73, v101, v101
	v_mul_f32_e32 v74, v102, v102
	v_mul_f32_e32 v75, v103, v103
	v_fmamk_f32 v72, v72, 0xbdd2d3e2, v215
	v_fmamk_f32 v73, v73, 0xbdd2d3e2, v215
	v_fmamk_f32 v74, v74, 0xbdd2d3e2, v215
	v_fmamk_f32 v75, v75, 0xbdd2d3e2, v215
	v_mul_f32_e32 v72, v100, v72
	v_mul_f32_e32 v73, v101, v73
	v_mul_f32_e32 v74, v102, v74
	v_mul_f32_e32 v75, v103, v75
	v_exp_f32_e32 v72, v72
	v_exp_f32_e32 v73, v73
	v_exp_f32_e32 v74, v74
	v_exp_f32_e32 v75, v75
	v_add_f32_e32 v72, 1.0, v72
	v_add_f32_e32 v73, 1.0, v73
	v_add_f32_e32 v74, 1.0, v74
	v_add_f32_e32 v75, 1.0, v75
	v_rcp_f32_e32 v72, v72
	v_rcp_f32_e32 v73, v73
	v_rcp_f32_e32 v74, v74
	v_rcp_f32_e32 v75, v75
	v_pk_mul_f32 v[72:73], v[100:101], v[72:73]
	s_nop 0
	v_pk_mul_f32 v[72:73], v[72:73], v[128:129]
	v_pk_mul_f32 v[74:75], v[102:103], v[74:75]
	s_nop 0
	v_pk_mul_f32 v[74:75], v[74:75], v[130:131]
	s_nop 0
	v_mul_f32_e32 v96, v76, v76
	v_mul_f32_e32 v97, v77, v77
	v_mul_f32_e32 v98, v78, v78
	v_mul_f32_e32 v99, v79, v79
	v_fmamk_f32 v96, v96, 0xbdd2d3e2, v215
	v_fmamk_f32 v97, v97, 0xbdd2d3e2, v215
	v_fmamk_f32 v98, v98, 0xbdd2d3e2, v215
	v_fmamk_f32 v99, v99, 0xbdd2d3e2, v215
	v_mul_f32_e32 v96, v76, v96
	v_mul_f32_e32 v97, v77, v97
	v_mul_f32_e32 v98, v78, v98
	v_mul_f32_e32 v99, v79, v99
	v_exp_f32_e32 v96, v96
	v_exp_f32_e32 v97, v97
	v_exp_f32_e32 v98, v98
	v_exp_f32_e32 v99, v99
	v_add_f32_e32 v96, 1.0, v96
	v_add_f32_e32 v97, 1.0, v97
	v_add_f32_e32 v98, 1.0, v98
	v_add_f32_e32 v99, 1.0, v99
	v_rcp_f32_e32 v96, v96
	v_rcp_f32_e32 v97, v97
	v_rcp_f32_e32 v98, v98
	v_rcp_f32_e32 v99, v99
	v_pk_mul_f32 v[76:77], v[76:77], v[96:97]
	s_nop 0
	v_pk_mul_f32 v[76:77], v[76:77], v[108:109]
	v_pk_mul_f32 v[78:79], v[78:79], v[98:99]
	s_nop 0
	v_pk_mul_f32 v[78:79], v[78:79], v[110:111]
	s_nop 0
	v_mul_f32_e32 v96, v120, v120
	v_mul_f32_e32 v97, v121, v121
	v_mul_f32_e32 v98, v122, v122
	v_mul_f32_e32 v99, v123, v123
	v_fmamk_f32 v96, v96, 0xbdd2d3e2, v215
	v_fmamk_f32 v97, v97, 0xbdd2d3e2, v215
	v_fmamk_f32 v98, v98, 0xbdd2d3e2, v215
	v_fmamk_f32 v99, v99, 0xbdd2d3e2, v215
	v_mul_f32_e32 v96, v120, v96
	v_mul_f32_e32 v97, v121, v97
	v_mul_f32_e32 v98, v122, v98
	v_mul_f32_e32 v99, v123, v99
	v_exp_f32_e32 v96, v96
	v_exp_f32_e32 v97, v97
	v_exp_f32_e32 v98, v98
	v_exp_f32_e32 v99, v99
	v_add_f32_e32 v96, 1.0, v96
	v_add_f32_e32 v97, 1.0, v97
	v_add_f32_e32 v98, 1.0, v98
	v_add_f32_e32 v99, 1.0, v99
	v_rcp_f32_e32 v96, v96
	v_rcp_f32_e32 v97, v97
	v_rcp_f32_e32 v98, v98
	v_rcp_f32_e32 v99, v99
	v_pk_mul_f32 v[96:97], v[120:121], v[96:97]
	s_nop 0
	v_pk_mul_f32 v[80:81], v[96:97], v[80:81]
	v_pk_mul_f32 v[98:99], v[122:123], v[98:99]
	s_nop 0
	v_pk_mul_f32 v[82:83], v[98:99], v[82:83]
	s_nop 0
	v_mul_f32_e32 v96, v116, v116
	v_mul_f32_e32 v97, v117, v117
	v_mul_f32_e32 v98, v118, v118
	v_mul_f32_e32 v99, v119, v119
	v_fmamk_f32 v96, v96, 0xbdd2d3e2, v215
	v_fmamk_f32 v97, v97, 0xbdd2d3e2, v215
	v_fmamk_f32 v98, v98, 0xbdd2d3e2, v215
	v_fmamk_f32 v99, v99, 0xbdd2d3e2, v215
	v_mul_f32_e32 v96, v116, v96
	v_mul_f32_e32 v97, v117, v97
	v_mul_f32_e32 v98, v118, v98
	v_mul_f32_e32 v99, v119, v99
	v_exp_f32_e32 v96, v96
	v_exp_f32_e32 v97, v97
	v_exp_f32_e32 v98, v98
	v_exp_f32_e32 v99, v99
	v_add_f32_e32 v96, 1.0, v96
	v_add_f32_e32 v97, 1.0, v97
	v_add_f32_e32 v98, 1.0, v98
	v_add_f32_e32 v99, 1.0, v99
	v_rcp_f32_e32 v96, v96
	v_rcp_f32_e32 v97, v97
	v_rcp_f32_e32 v98, v98
	v_rcp_f32_e32 v99, v99
	v_pk_mul_f32 v[96:97], v[116:117], v[96:97]
	s_nop 0
	v_pk_mul_f32 v[84:85], v[96:97], v[84:85]
	v_pk_mul_f32 v[98:99], v[118:119], v[98:99]
	s_nop 0
	v_pk_mul_f32 v[86:87], v[98:99], v[86:87]
	s_nop 0
	v_mul_f32_e32 v96, v112, v112
	v_mul_f32_e32 v97, v113, v113
	v_mul_f32_e32 v98, v114, v114
	v_mul_f32_e32 v99, v115, v115
	v_fmamk_f32 v96, v96, 0xbdd2d3e2, v215
	v_fmamk_f32 v97, v97, 0xbdd2d3e2, v215
	v_fmamk_f32 v98, v98, 0xbdd2d3e2, v215
	v_fmamk_f32 v99, v99, 0xbdd2d3e2, v215
	v_mul_f32_e32 v96, v112, v96
	v_mul_f32_e32 v97, v113, v97
	v_mul_f32_e32 v98, v114, v98
	v_mul_f32_e32 v99, v115, v99
	v_exp_f32_e32 v96, v96
	v_exp_f32_e32 v97, v97
	v_exp_f32_e32 v98, v98
	v_exp_f32_e32 v99, v99
	v_add_f32_e32 v96, 1.0, v96
	v_add_f32_e32 v97, 1.0, v97
	v_add_f32_e32 v98, 1.0, v98
	v_add_f32_e32 v99, 1.0, v99
	v_rcp_f32_e32 v96, v96
	v_rcp_f32_e32 v97, v97
	v_rcp_f32_e32 v98, v98
	v_rcp_f32_e32 v99, v99
	v_pk_mul_f32 v[96:97], v[112:113], v[96:97]
	s_nop 0
	v_pk_mul_f32 v[88:89], v[96:97], v[88:89]
	v_pk_mul_f32 v[98:99], v[114:115], v[98:99]
	s_nop 0
	v_pk_mul_f32 v[90:91], v[98:99], v[90:91]
	s_nop 0
	v_mul_f32_e32 v96, v92, v92
	v_mul_f32_e32 v97, v93, v93
	v_mul_f32_e32 v98, v94, v94
	v_mul_f32_e32 v99, v95, v95
	v_fmamk_f32 v96, v96, 0xbdd2d3e2, v215
	v_fmamk_f32 v97, v97, 0xbdd2d3e2, v215
	v_fmamk_f32 v98, v98, 0xbdd2d3e2, v215
	v_fmamk_f32 v99, v99, 0xbdd2d3e2, v215
	v_mul_f32_e32 v96, v92, v96
	v_mul_f32_e32 v97, v93, v97
	v_mul_f32_e32 v98, v94, v98
	v_mul_f32_e32 v99, v95, v99
	v_exp_f32_e32 v96, v96
	v_exp_f32_e32 v97, v97
	v_exp_f32_e32 v98, v98
	v_exp_f32_e32 v99, v99
	v_add_f32_e32 v96, 1.0, v96
	v_add_f32_e32 v97, 1.0, v97
	v_add_f32_e32 v98, 1.0, v98
	v_add_f32_e32 v99, 1.0, v99
	v_rcp_f32_e32 v96, v96
	v_rcp_f32_e32 v97, v97
	v_rcp_f32_e32 v98, v98
	v_rcp_f32_e32 v99, v99
	v_pk_mul_f32 v[92:93], v[92:93], v[96:97]
	s_nop 0
	v_pk_mul_f32 v[92:93], v[92:93], v[104:105]
	v_pk_mul_f32 v[94:95], v[94:95], v[98:99]
	s_nop 0
	v_pk_mul_f32 v[94:95], v[94:95], v[106:107]
	s_nop 0
	v_or_b32_e32 v96, 4, v204
	v_ashrrev_i32_e32 v97, 31, v96
	v_lshlrev_b64 v[96:97], 2, v[96:97]
	v_lshl_add_u64 v[98:99], s[36:37], 0, v[96:97]
	ds_read_b128 v[114:117], v220 offset:12304
	v_lshl_add_u64 v[96:97], s[38:39], 0, v[96:97]
	ds_read_b128 v[110:113], v220 offset:13328
	ds_read_b128 v[106:109], v220 offset:16
	ds_read_b128 v[118:121], v220 offset:1040
	v_mov_b32_e32 v104, 0
	s_and_b64 vcc, exec, s[8:9]
	v_mov_b32_e32 v100, 0
	v_mov_b32_e32 v101, 0
	v_mov_b32_e32 v102, 0
	v_mov_b32_e32 v103, 0
	s_cbranch_vccnz .LBB0_995
	ds_read_b128 v[100:103], v212 offset:16
.LBB0_995:
	v_mov_b64_e32 v[98:99], v[46:47]
	v_mov_b64_e32 v[96:97], v[44:45]
	s_nop 1
	v_mov_b32_dpp v122, v96 row_ror:1 row_mask:0xf bank_mask:0xf bound_ctrl:1
	v_mov_b32_dpp v96, v96 row_ror:2 row_mask:0xf bank_mask:0xf bound_ctrl:1
	v_mov_b32_dpp v123, v97 row_ror:1 row_mask:0xf bank_mask:0xf bound_ctrl:1
	v_mov_b32_dpp v97, v97 row_ror:2 row_mask:0xf bank_mask:0xf bound_ctrl:1
	v_mov_b32_dpp v124, v98 row_ror:1 row_mask:0xf bank_mask:0xf bound_ctrl:1
	v_mov_b32_dpp v98, v98 row_ror:2 row_mask:0xf bank_mask:0xf bound_ctrl:1
	v_mov_b32_dpp v125, v99 row_ror:1 row_mask:0xf bank_mask:0xf bound_ctrl:1
	v_mov_b32_dpp v99, v99 row_ror:2 row_mask:0xf bank_mask:0xf bound_ctrl:1
	v_mov_b32_dpp v122, v52 row_shr:1 row_mask:0xf bank_mask:0xf
	v_mov_b32_dpp v96, v52 row_shr:2 row_mask:0xf bank_mask:0xf
	v_mov_b32_dpp v123, v53 row_shr:1 row_mask:0xf bank_mask:0xf
	v_mov_b32_dpp v97, v53 row_shr:2 row_mask:0xf bank_mask:0xf
	v_mov_b32_dpp v124, v54 row_shr:1 row_mask:0xf bank_mask:0xf
	v_mov_b32_dpp v98, v54 row_shr:2 row_mask:0xf bank_mask:0xf
	v_mov_b32_dpp v125, v55 row_shr:1 row_mask:0xf bank_mask:0xf
	v_mov_b32_dpp v99, v55 row_shr:2 row_mask:0xf bank_mask:0xf
	s_waitcnt lgkmcnt(0)
	v_pk_fma_f32 v[54:55], v[116:117], v[54:55], v[120:121]
	v_pk_fma_f32 v[52:53], v[114:115], v[52:53], v[118:119]
	v_pk_fma_f32 v[54:55], v[112:113], v[124:125], v[54:55]
	v_pk_fma_f32 v[52:53], v[110:111], v[122:123], v[52:53]
	v_pk_fma_f32 v[54:55], v[108:109], v[98:99], v[54:55]
	v_pk_fma_f32 v[52:53], v[106:107], v[96:97], v[52:53]
	s_nop 0
	v_mov_b64_e32 v[98:99], v[34:35]
	v_mov_b64_e32 v[96:97], v[32:33]
	s_nop 1
	v_mov_b32_dpp v122, v96 row_ror:1 row_mask:0xf bank_mask:0xf bound_ctrl:1
	v_mov_b32_dpp v96, v96 row_ror:2 row_mask:0xf bank_mask:0xf bound_ctrl:1
	v_mov_b32_dpp v123, v97 row_ror:1 row_mask:0xf bank_mask:0xf bound_ctrl:1
	v_mov_b32_dpp v97, v97 row_ror:2 row_mask:0xf bank_mask:0xf bound_ctrl:1
	v_mov_b32_dpp v124, v98 row_ror:1 row_mask:0xf bank_mask:0xf bound_ctrl:1
	v_mov_b32_dpp v98, v98 row_ror:2 row_mask:0xf bank_mask:0xf bound_ctrl:1
	v_mov_b32_dpp v125, v99 row_ror:1 row_mask:0xf bank_mask:0xf bound_ctrl:1
	v_mov_b32_dpp v99, v99 row_ror:2 row_mask:0xf bank_mask:0xf bound_ctrl:1
	v_mov_b32_dpp v122, v44 row_shr:1 row_mask:0xf bank_mask:0xf
	v_mov_b32_dpp v96, v44 row_shr:2 row_mask:0xf bank_mask:0xf
	v_mov_b32_dpp v123, v45 row_shr:1 row_mask:0xf bank_mask:0xf
	v_mov_b32_dpp v97, v45 row_shr:2 row_mask:0xf bank_mask:0xf
	v_mov_b32_dpp v124, v46 row_shr:1 row_mask:0xf bank_mask:0xf
	v_mov_b32_dpp v98, v46 row_shr:2 row_mask:0xf bank_mask:0xf
	v_mov_b32_dpp v125, v47 row_shr:1 row_mask:0xf bank_mask:0xf
	v_mov_b32_dpp v99, v47 row_shr:2 row_mask:0xf bank_mask:0xf
	v_pk_fma_f32 v[46:47], v[116:117], v[46:47], v[120:121]
	v_pk_fma_f32 v[44:45], v[114:115], v[44:45], v[118:119]
	v_pk_fma_f32 v[46:47], v[112:113], v[124:125], v[46:47]
	v_pk_fma_f32 v[44:45], v[110:111], v[122:123], v[44:45]
	v_pk_fma_f32 v[46:47], v[108:109], v[98:99], v[46:47]
	v_pk_fma_f32 v[44:45], v[106:107], v[96:97], v[44:45]
	s_nop 0
	v_mov_b64_e32 v[98:99], v[26:27]
	v_mov_b64_e32 v[96:97], v[24:25]
	s_nop 1
	v_mov_b32_dpp v122, v96 row_ror:1 row_mask:0xf bank_mask:0xf bound_ctrl:1
	v_mov_b32_dpp v96, v96 row_ror:2 row_mask:0xf bank_mask:0xf bound_ctrl:1
	v_mov_b32_dpp v123, v97 row_ror:1 row_mask:0xf bank_mask:0xf bound_ctrl:1
	v_mov_b32_dpp v97, v97 row_ror:2 row_mask:0xf bank_mask:0xf bound_ctrl:1
	v_mov_b32_dpp v124, v98 row_ror:1 row_mask:0xf bank_mask:0xf bound_ctrl:1
	v_mov_b32_dpp v98, v98 row_ror:2 row_mask:0xf bank_mask:0xf bound_ctrl:1
	v_mov_b32_dpp v125, v99 row_ror:1 row_mask:0xf bank_mask:0xf bound_ctrl:1
	v_mov_b32_dpp v99, v99 row_ror:2 row_mask:0xf bank_mask:0xf bound_ctrl:1
	v_mov_b32_dpp v122, v32 row_shr:1 row_mask:0xf bank_mask:0xf
	v_mov_b32_dpp v96, v32 row_shr:2 row_mask:0xf bank_mask:0xf
	v_mov_b32_dpp v123, v33 row_shr:1 row_mask:0xf bank_mask:0xf
	v_mov_b32_dpp v97, v33 row_shr:2 row_mask:0xf bank_mask:0xf
	v_mov_b32_dpp v124, v34 row_shr:1 row_mask:0xf bank_mask:0xf
	v_mov_b32_dpp v98, v34 row_shr:2 row_mask:0xf bank_mask:0xf
	v_mov_b32_dpp v125, v35 row_shr:1 row_mask:0xf bank_mask:0xf
	v_mov_b32_dpp v99, v35 row_shr:2 row_mask:0xf bank_mask:0xf
	v_pk_fma_f32 v[34:35], v[116:117], v[34:35], v[120:121]
	v_pk_fma_f32 v[32:33], v[114:115], v[32:33], v[118:119]
	v_pk_fma_f32 v[34:35], v[112:113], v[124:125], v[34:35]
	v_pk_fma_f32 v[32:33], v[110:111], v[122:123], v[32:33]
	v_pk_fma_f32 v[98:99], v[108:109], v[98:99], v[34:35]
	v_pk_fma_f32 v[96:97], v[106:107], v[96:97], v[32:33]
	s_nop 0
	s_waitcnt lgkmcnt(0)
	s_nop 1
	v_mov_b32_dpp v32, v100 row_ror:1 row_mask:0xf bank_mask:0xf bound_ctrl:1
	v_mov_b32_dpp v34, v100 row_ror:2 row_mask:0xf bank_mask:0xf bound_ctrl:1
	v_mov_b32_dpp v33, v101 row_ror:1 row_mask:0xf bank_mask:0xf bound_ctrl:1
	v_mov_b32_dpp v35, v101 row_ror:2 row_mask:0xf bank_mask:0xf bound_ctrl:1
	v_mov_b32_dpp v100, v102 row_ror:1 row_mask:0xf bank_mask:0xf bound_ctrl:1
	v_mov_b32_dpp v102, v102 row_ror:2 row_mask:0xf bank_mask:0xf bound_ctrl:1
	v_mov_b32_dpp v101, v103 row_ror:1 row_mask:0xf bank_mask:0xf bound_ctrl:1
	v_mov_b32_dpp v103, v103 row_ror:2 row_mask:0xf bank_mask:0xf bound_ctrl:1
	v_mov_b32_dpp v32, v24 row_shr:1 row_mask:0xf bank_mask:0xf
	v_mov_b32_dpp v34, v24 row_shr:2 row_mask:0xf bank_mask:0xf
	v_mov_b32_dpp v33, v25 row_shr:1 row_mask:0xf bank_mask:0xf
	v_mov_b32_dpp v35, v25 row_shr:2 row_mask:0xf bank_mask:0xf
	v_mov_b32_dpp v100, v26 row_shr:1 row_mask:0xf bank_mask:0xf
	v_mov_b32_dpp v102, v26 row_shr:2 row_mask:0xf bank_mask:0xf
	v_mov_b32_dpp v101, v27 row_shr:1 row_mask:0xf bank_mask:0xf
	v_mov_b32_dpp v103, v27 row_shr:2 row_mask:0xf bank_mask:0xf
	v_pk_fma_f32 v[26:27], v[116:117], v[26:27], v[120:121]
	v_pk_fma_f32 v[24:25], v[114:115], v[24:25], v[118:119]
	v_pk_fma_f32 v[26:27], v[112:113], v[100:101], v[26:27]
	v_pk_fma_f32 v[24:25], v[110:111], v[32:33], v[24:25]
	v_pk_fma_f32 v[102:103], v[108:109], v[102:103], v[26:27]
	v_pk_fma_f32 v[100:101], v[106:107], v[34:35], v[24:25]
	s_nop 0
	v_mov_b64_e32 v[24:25], v[56:57]
	v_mov_b64_e32 v[26:27], v[58:59]
	ds_read_b128 v[122:125], v212 offset:4112
	s_nop 1
	v_mov_b32_dpp v32, v24 row_ror:1 row_mask:0xf bank_mask:0xf bound_ctrl:1
	v_mov_b32_dpp v24, v24 row_ror:2 row_mask:0xf bank_mask:0xf bound_ctrl:1
	v_mov_b32_dpp v33, v25 row_ror:1 row_mask:0xf bank_mask:0xf bound_ctrl:1
	v_mov_b32_dpp v25, v25 row_ror:2 row_mask:0xf bank_mask:0xf bound_ctrl:1
	v_mov_b32_dpp v34, v26 row_ror:1 row_mask:0xf bank_mask:0xf bound_ctrl:1
	v_mov_b32_dpp v26, v26 row_ror:2 row_mask:0xf bank_mask:0xf bound_ctrl:1
	v_mov_b32_dpp v35, v27 row_ror:1 row_mask:0xf bank_mask:0xf bound_ctrl:1
	v_mov_b32_dpp v27, v27 row_ror:2 row_mask:0xf bank_mask:0xf bound_ctrl:1
	v_mov_b32_dpp v32, v60 row_shr:1 row_mask:0xf bank_mask:0xf
	v_mov_b32_dpp v24, v60 row_shr:2 row_mask:0xf bank_mask:0xf
	v_mov_b32_dpp v33, v61 row_shr:1 row_mask:0xf bank_mask:0xf
	v_mov_b32_dpp v25, v61 row_shr:2 row_mask:0xf bank_mask:0xf
	v_mov_b32_dpp v34, v62 row_shr:1 row_mask:0xf bank_mask:0xf
	v_mov_b32_dpp v26, v62 row_shr:2 row_mask:0xf bank_mask:0xf
	v_mov_b32_dpp v35, v63 row_shr:1 row_mask:0xf bank_mask:0xf
	v_mov_b32_dpp v27, v63 row_shr:2 row_mask:0xf bank_mask:0xf
	v_pk_fma_f32 v[62:63], v[116:117], v[62:63], v[120:121]
	v_pk_fma_f32 v[60:61], v[114:115], v[60:61], v[118:119]
	v_pk_fma_f32 v[34:35], v[112:113], v[34:35], v[62:63]
	v_pk_fma_f32 v[32:33], v[110:111], v[32:33], v[60:61]
	v_pk_fma_f32 v[26:27], v[108:109], v[26:27], v[34:35]
	v_pk_fma_f32 v[24:25], v[106:107], v[24:25], v[32:33]
	s_nop 0
	v_mov_b64_e32 v[32:33], v[48:49]
	v_mov_b64_e32 v[34:35], v[50:51]
	s_nop 1
	v_mov_b32_dpp v60, v32 row_ror:1 row_mask:0xf bank_mask:0xf bound_ctrl:1
	v_mov_b32_dpp v32, v32 row_ror:2 row_mask:0xf bank_mask:0xf bound_ctrl:1
	v_mov_b32_dpp v61, v33 row_ror:1 row_mask:0xf bank_mask:0xf bound_ctrl:1
	v_mov_b32_dpp v33, v33 row_ror:2 row_mask:0xf bank_mask:0xf bound_ctrl:1
	v_mov_b32_dpp v62, v34 row_ror:1 row_mask:0xf bank_mask:0xf bound_ctrl:1
	v_mov_b32_dpp v34, v34 row_ror:2 row_mask:0xf bank_mask:0xf bound_ctrl:1
	v_mov_b32_dpp v63, v35 row_ror:1 row_mask:0xf bank_mask:0xf bound_ctrl:1
	v_mov_b32_dpp v35, v35 row_ror:2 row_mask:0xf bank_mask:0xf bound_ctrl:1
	v_mov_b32_dpp v60, v56 row_shr:1 row_mask:0xf bank_mask:0xf
	v_mov_b32_dpp v32, v56 row_shr:2 row_mask:0xf bank_mask:0xf
	v_mov_b32_dpp v61, v57 row_shr:1 row_mask:0xf bank_mask:0xf
	v_mov_b32_dpp v33, v57 row_shr:2 row_mask:0xf bank_mask:0xf
	v_mov_b32_dpp v62, v58 row_shr:1 row_mask:0xf bank_mask:0xf
	v_mov_b32_dpp v34, v58 row_shr:2 row_mask:0xf bank_mask:0xf
	v_mov_b32_dpp v63, v59 row_shr:1 row_mask:0xf bank_mask:0xf
	v_mov_b32_dpp v35, v59 row_shr:2 row_mask:0xf bank_mask:0xf
	v_pk_fma_f32 v[58:59], v[116:117], v[58:59], v[120:121]
	v_pk_fma_f32 v[56:57], v[114:115], v[56:57], v[118:119]
	v_pk_fma_f32 v[58:59], v[112:113], v[62:63], v[58:59]
	v_pk_fma_f32 v[56:57], v[110:111], v[60:61], v[56:57]
	v_pk_fma_f32 v[34:35], v[108:109], v[34:35], v[58:59]
	v_pk_fma_f32 v[32:33], v[106:107], v[32:33], v[56:57]
	s_nop 0
	v_mov_b64_e32 v[58:59], v[42:43]
	v_mov_b64_e32 v[56:57], v[40:41]
	s_nop 1
	v_mov_b32_dpp v60, v56 row_ror:1 row_mask:0xf bank_mask:0xf bound_ctrl:1
	v_mov_b32_dpp v56, v56 row_ror:2 row_mask:0xf bank_mask:0xf bound_ctrl:1
	v_mov_b32_dpp v61, v57 row_ror:1 row_mask:0xf bank_mask:0xf bound_ctrl:1
	v_mov_b32_dpp v57, v57 row_ror:2 row_mask:0xf bank_mask:0xf bound_ctrl:1
	v_mov_b32_dpp v62, v58 row_ror:1 row_mask:0xf bank_mask:0xf bound_ctrl:1
	v_mov_b32_dpp v58, v58 row_ror:2 row_mask:0xf bank_mask:0xf bound_ctrl:1
	v_mov_b32_dpp v63, v59 row_ror:1 row_mask:0xf bank_mask:0xf bound_ctrl:1
	v_mov_b32_dpp v59, v59 row_ror:2 row_mask:0xf bank_mask:0xf bound_ctrl:1
	v_mov_b32_dpp v60, v48 row_shr:1 row_mask:0xf bank_mask:0xf
	v_mov_b32_dpp v56, v48 row_shr:2 row_mask:0xf bank_mask:0xf
	v_mov_b32_dpp v61, v49 row_shr:1 row_mask:0xf bank_mask:0xf
	v_mov_b32_dpp v57, v49 row_shr:2 row_mask:0xf bank_mask:0xf
	v_mov_b32_dpp v62, v50 row_shr:1 row_mask:0xf bank_mask:0xf
	v_mov_b32_dpp v58, v50 row_shr:2 row_mask:0xf bank_mask:0xf
	v_mov_b32_dpp v63, v51 row_shr:1 row_mask:0xf bank_mask:0xf
	v_mov_b32_dpp v59, v51 row_shr:2 row_mask:0xf bank_mask:0xf
	v_pk_fma_f32 v[50:51], v[116:117], v[50:51], v[120:121]
	v_pk_fma_f32 v[48:49], v[114:115], v[48:49], v[118:119]
	v_pk_fma_f32 v[50:51], v[112:113], v[62:63], v[50:51]
	v_pk_fma_f32 v[48:49], v[110:111], v[60:61], v[48:49]
	v_pk_fma_f32 v[50:51], v[108:109], v[58:59], v[50:51]
	v_pk_fma_f32 v[48:49], v[106:107], v[56:57], v[48:49]
	s_nop 0
	s_waitcnt lgkmcnt(0)
	s_nop 1
	v_mov_b32_dpp v56, v122 row_ror:1 row_mask:0xf bank_mask:0xf bound_ctrl:1
	v_mov_b32_dpp v58, v122 row_ror:2 row_mask:0xf bank_mask:0xf bound_ctrl:1
	v_mov_b32_dpp v57, v123 row_ror:1 row_mask:0xf bank_mask:0xf bound_ctrl:1
	v_mov_b32_dpp v59, v123 row_ror:2 row_mask:0xf bank_mask:0xf bound_ctrl:1
	v_mov_b32_dpp v60, v124 row_ror:1 row_mask:0xf bank_mask:0xf bound_ctrl:1
	v_mov_b32_dpp v62, v124 row_ror:2 row_mask:0xf bank_mask:0xf bound_ctrl:1
	v_mov_b32_dpp v61, v125 row_ror:1 row_mask:0xf bank_mask:0xf bound_ctrl:1
	v_mov_b32_dpp v63, v125 row_ror:2 row_mask:0xf bank_mask:0xf bound_ctrl:1
	v_mov_b32_dpp v56, v40 row_shr:1 row_mask:0xf bank_mask:0xf
	v_mov_b32_dpp v58, v40 row_shr:2 row_mask:0xf bank_mask:0xf
	v_mov_b32_dpp v57, v41 row_shr:1 row_mask:0xf bank_mask:0xf
	v_mov_b32_dpp v59, v41 row_shr:2 row_mask:0xf bank_mask:0xf
	v_mov_b32_dpp v60, v42 row_shr:1 row_mask:0xf bank_mask:0xf
	v_mov_b32_dpp v62, v42 row_shr:2 row_mask:0xf bank_mask:0xf
	v_mov_b32_dpp v61, v43 row_shr:1 row_mask:0xf bank_mask:0xf
	v_mov_b32_dpp v63, v43 row_shr:2 row_mask:0xf bank_mask:0xf
	v_pk_fma_f32 v[42:43], v[116:117], v[42:43], v[120:121]
	v_pk_fma_f32 v[40:41], v[114:115], v[40:41], v[118:119]
	v_pk_fma_f32 v[42:43], v[112:113], v[60:61], v[42:43]
	v_pk_fma_f32 v[40:41], v[110:111], v[56:57], v[40:41]
	v_pk_fma_f32 v[42:43], v[108:109], v[62:63], v[42:43]
	v_pk_fma_f32 v[40:41], v[106:107], v[58:59], v[40:41]
	s_nop 0
	v_add_u32_e32 v56, 0xc04, v204
	v_ashrrev_i32_e32 v57, 31, v56
	v_lshlrev_b64 v[106:107], 2, v[56:57]
	v_lshl_add_u64 v[56:57], s[24:25], 0, v[106:107]
	v_lshl_add_u64 v[58:59], s[36:37], 0, v[106:107]
	ds_read_b128 v[108:111], v220 offset:12816
	ds_read_b128 v[60:63], v220 offset:13840
	v_lshl_add_u64 v[56:57], s[38:39], 0, v[106:107]
	v_lshl_add_u64 v[106:107], s[26:27], 0, v[106:107]
	ds_read_b128 v[56:59], v220 offset:528
	s_and_b64 vcc, exec, s[8:9]
	ds_read_b128 v[112:115], v220 offset:1552
	v_mov_b32_e32 v105, 0
	v_mov_b32_e32 v106, 0
	v_mov_b32_e32 v107, 0
	s_cbranch_vccnz .LBB0_997
	ds_read_b128 v[104:107], v212 offset:528
.LBB0_997:
	v_mov_b64_e32 v[118:119], v[14:15]
	v_mov_b64_e32 v[116:117], v[12:13]
	s_nop 1
	v_mov_b32_dpp v120, v116 row_ror:1 row_mask:0xf bank_mask:0xf bound_ctrl:1
	v_mov_b32_dpp v116, v116 row_ror:2 row_mask:0xf bank_mask:0xf bound_ctrl:1
	v_mov_b32_dpp v121, v117 row_ror:1 row_mask:0xf bank_mask:0xf bound_ctrl:1
	v_mov_b32_dpp v117, v117 row_ror:2 row_mask:0xf bank_mask:0xf bound_ctrl:1
	v_mov_b32_dpp v122, v118 row_ror:1 row_mask:0xf bank_mask:0xf bound_ctrl:1
	v_mov_b32_dpp v118, v118 row_ror:2 row_mask:0xf bank_mask:0xf bound_ctrl:1
	v_mov_b32_dpp v123, v119 row_ror:1 row_mask:0xf bank_mask:0xf bound_ctrl:1
	v_mov_b32_dpp v119, v119 row_ror:2 row_mask:0xf bank_mask:0xf bound_ctrl:1
	v_mov_b32_dpp v120, v20 row_shr:1 row_mask:0xf bank_mask:0xf
	v_mov_b32_dpp v116, v20 row_shr:2 row_mask:0xf bank_mask:0xf
	v_mov_b32_dpp v121, v21 row_shr:1 row_mask:0xf bank_mask:0xf
	v_mov_b32_dpp v117, v21 row_shr:2 row_mask:0xf bank_mask:0xf
	v_mov_b32_dpp v122, v22 row_shr:1 row_mask:0xf bank_mask:0xf
	v_mov_b32_dpp v118, v22 row_shr:2 row_mask:0xf bank_mask:0xf
	v_mov_b32_dpp v123, v23 row_shr:1 row_mask:0xf bank_mask:0xf
	v_mov_b32_dpp v119, v23 row_shr:2 row_mask:0xf bank_mask:0xf
	s_waitcnt lgkmcnt(0)
	v_pk_fma_f32 v[22:23], v[110:111], v[22:23], v[114:115]
	v_pk_fma_f32 v[20:21], v[108:109], v[20:21], v[112:113]
	v_pk_fma_f32 v[22:23], v[62:63], v[122:123], v[22:23]
	v_pk_fma_f32 v[20:21], v[60:61], v[120:121], v[20:21]
	v_pk_fma_f32 v[22:23], v[58:59], v[118:119], v[22:23]
	v_pk_fma_f32 v[20:21], v[56:57], v[116:117], v[20:21]
	s_nop 0
	v_mov_b64_e32 v[118:119], v[6:7]
	v_mov_b64_e32 v[116:117], v[4:5]
	s_nop 1
	v_mov_b32_dpp v120, v116 row_ror:1 row_mask:0xf bank_mask:0xf bound_ctrl:1
	v_mov_b32_dpp v116, v116 row_ror:2 row_mask:0xf bank_mask:0xf bound_ctrl:1
	v_mov_b32_dpp v121, v117 row_ror:1 row_mask:0xf bank_mask:0xf bound_ctrl:1
	v_mov_b32_dpp v117, v117 row_ror:2 row_mask:0xf bank_mask:0xf bound_ctrl:1
	v_mov_b32_dpp v122, v118 row_ror:1 row_mask:0xf bank_mask:0xf bound_ctrl:1
	v_mov_b32_dpp v118, v118 row_ror:2 row_mask:0xf bank_mask:0xf bound_ctrl:1
	v_mov_b32_dpp v123, v119 row_ror:1 row_mask:0xf bank_mask:0xf bound_ctrl:1
	v_mov_b32_dpp v119, v119 row_ror:2 row_mask:0xf bank_mask:0xf bound_ctrl:1
	v_mov_b32_dpp v120, v12 row_shr:1 row_mask:0xf bank_mask:0xf
	v_mov_b32_dpp v116, v12 row_shr:2 row_mask:0xf bank_mask:0xf
	v_mov_b32_dpp v121, v13 row_shr:1 row_mask:0xf bank_mask:0xf
	v_mov_b32_dpp v117, v13 row_shr:2 row_mask:0xf bank_mask:0xf
	v_mov_b32_dpp v122, v14 row_shr:1 row_mask:0xf bank_mask:0xf
	v_mov_b32_dpp v118, v14 row_shr:2 row_mask:0xf bank_mask:0xf
	v_mov_b32_dpp v123, v15 row_shr:1 row_mask:0xf bank_mask:0xf
	v_mov_b32_dpp v119, v15 row_shr:2 row_mask:0xf bank_mask:0xf
	v_pk_fma_f32 v[14:15], v[110:111], v[14:15], v[114:115]
	v_pk_fma_f32 v[12:13], v[108:109], v[12:13], v[112:113]
	v_pk_fma_f32 v[14:15], v[62:63], v[122:123], v[14:15]
	v_pk_fma_f32 v[12:13], v[60:61], v[120:121], v[12:13]
	v_pk_fma_f32 v[14:15], v[58:59], v[118:119], v[14:15]
	v_pk_fma_f32 v[12:13], v[56:57], v[116:117], v[12:13]
	s_nop 0
	v_mov_b64_e32 v[118:119], v[2:3]
	v_mov_b64_e32 v[116:117], v[0:1]
	s_nop 1
	v_mov_b32_dpp v120, v116 row_ror:1 row_mask:0xf bank_mask:0xf bound_ctrl:1
	v_mov_b32_dpp v116, v116 row_ror:2 row_mask:0xf bank_mask:0xf bound_ctrl:1
	v_mov_b32_dpp v121, v117 row_ror:1 row_mask:0xf bank_mask:0xf bound_ctrl:1
	v_mov_b32_dpp v117, v117 row_ror:2 row_mask:0xf bank_mask:0xf bound_ctrl:1
	v_mov_b32_dpp v122, v118 row_ror:1 row_mask:0xf bank_mask:0xf bound_ctrl:1
	v_mov_b32_dpp v118, v118 row_ror:2 row_mask:0xf bank_mask:0xf bound_ctrl:1
	v_mov_b32_dpp v123, v119 row_ror:1 row_mask:0xf bank_mask:0xf bound_ctrl:1
	v_mov_b32_dpp v119, v119 row_ror:2 row_mask:0xf bank_mask:0xf bound_ctrl:1
	v_mov_b32_dpp v120, v4 row_shr:1 row_mask:0xf bank_mask:0xf
	v_mov_b32_dpp v116, v4 row_shr:2 row_mask:0xf bank_mask:0xf
	v_mov_b32_dpp v121, v5 row_shr:1 row_mask:0xf bank_mask:0xf
	v_mov_b32_dpp v117, v5 row_shr:2 row_mask:0xf bank_mask:0xf
	v_mov_b32_dpp v122, v6 row_shr:1 row_mask:0xf bank_mask:0xf
	v_mov_b32_dpp v118, v6 row_shr:2 row_mask:0xf bank_mask:0xf
	v_mov_b32_dpp v123, v7 row_shr:1 row_mask:0xf bank_mask:0xf
	v_mov_b32_dpp v119, v7 row_shr:2 row_mask:0xf bank_mask:0xf
	v_pk_fma_f32 v[6:7], v[110:111], v[6:7], v[114:115]
	v_pk_fma_f32 v[4:5], v[108:109], v[4:5], v[112:113]
	v_pk_fma_f32 v[6:7], v[62:63], v[122:123], v[6:7]
	v_pk_fma_f32 v[4:5], v[60:61], v[120:121], v[4:5]
	v_pk_fma_f32 v[118:119], v[58:59], v[118:119], v[6:7]
	v_pk_fma_f32 v[116:117], v[56:57], v[116:117], v[4:5]
	s_nop 0
	s_waitcnt lgkmcnt(0)
	s_nop 1
	v_mov_b32_dpp v4, v104 row_ror:1 row_mask:0xf bank_mask:0xf bound_ctrl:1
	v_mov_b32_dpp v6, v104 row_ror:2 row_mask:0xf bank_mask:0xf bound_ctrl:1
	v_mov_b32_dpp v5, v105 row_ror:1 row_mask:0xf bank_mask:0xf bound_ctrl:1
	v_mov_b32_dpp v7, v105 row_ror:2 row_mask:0xf bank_mask:0xf bound_ctrl:1
	v_mov_b32_dpp v104, v106 row_ror:1 row_mask:0xf bank_mask:0xf bound_ctrl:1
	v_mov_b32_dpp v106, v106 row_ror:2 row_mask:0xf bank_mask:0xf bound_ctrl:1
	v_mov_b32_dpp v105, v107 row_ror:1 row_mask:0xf bank_mask:0xf bound_ctrl:1
	v_mov_b32_dpp v107, v107 row_ror:2 row_mask:0xf bank_mask:0xf bound_ctrl:1
	v_mov_b32_dpp v4, v0 row_shr:1 row_mask:0xf bank_mask:0xf
	v_mov_b32_dpp v6, v0 row_shr:2 row_mask:0xf bank_mask:0xf
	v_mov_b32_dpp v5, v1 row_shr:1 row_mask:0xf bank_mask:0xf
	v_mov_b32_dpp v7, v1 row_shr:2 row_mask:0xf bank_mask:0xf
	v_mov_b32_dpp v104, v2 row_shr:1 row_mask:0xf bank_mask:0xf
	v_mov_b32_dpp v106, v2 row_shr:2 row_mask:0xf bank_mask:0xf
	v_mov_b32_dpp v105, v3 row_shr:1 row_mask:0xf bank_mask:0xf
	v_mov_b32_dpp v107, v3 row_shr:2 row_mask:0xf bank_mask:0xf
	v_pk_fma_f32 v[2:3], v[110:111], v[2:3], v[114:115]
	v_pk_fma_f32 v[0:1], v[108:109], v[0:1], v[112:113]
	v_pk_fma_f32 v[2:3], v[62:63], v[104:105], v[2:3]
	v_pk_fma_f32 v[0:1], v[60:61], v[4:5], v[0:1]
	v_pk_fma_f32 v[106:107], v[58:59], v[106:107], v[2:3]
	v_pk_fma_f32 v[104:105], v[56:57], v[6:7], v[0:1]
	s_nop 0
	v_mov_b64_e32 v[0:1], v[28:29]
	v_mov_b64_e32 v[2:3], v[30:31]
	ds_read_b128 v[120:123], v212 offset:4624
	s_nop 1
	v_mov_b32_dpp v4, v0 row_ror:1 row_mask:0xf bank_mask:0xf bound_ctrl:1
	v_mov_b32_dpp v0, v0 row_ror:2 row_mask:0xf bank_mask:0xf bound_ctrl:1
	v_mov_b32_dpp v5, v1 row_ror:1 row_mask:0xf bank_mask:0xf bound_ctrl:1
	v_mov_b32_dpp v1, v1 row_ror:2 row_mask:0xf bank_mask:0xf bound_ctrl:1
	v_mov_b32_dpp v6, v2 row_ror:1 row_mask:0xf bank_mask:0xf bound_ctrl:1
	v_mov_b32_dpp v2, v2 row_ror:2 row_mask:0xf bank_mask:0xf bound_ctrl:1
	v_mov_b32_dpp v7, v3 row_ror:1 row_mask:0xf bank_mask:0xf bound_ctrl:1
	v_mov_b32_dpp v3, v3 row_ror:2 row_mask:0xf bank_mask:0xf bound_ctrl:1
	v_mov_b32_dpp v4, v36 row_shr:1 row_mask:0xf bank_mask:0xf
	v_mov_b32_dpp v0, v36 row_shr:2 row_mask:0xf bank_mask:0xf
	v_mov_b32_dpp v5, v37 row_shr:1 row_mask:0xf bank_mask:0xf
	v_mov_b32_dpp v1, v37 row_shr:2 row_mask:0xf bank_mask:0xf
	v_mov_b32_dpp v6, v38 row_shr:1 row_mask:0xf bank_mask:0xf
	v_mov_b32_dpp v2, v38 row_shr:2 row_mask:0xf bank_mask:0xf
	v_mov_b32_dpp v7, v39 row_shr:1 row_mask:0xf bank_mask:0xf
	v_mov_b32_dpp v3, v39 row_shr:2 row_mask:0xf bank_mask:0xf
	v_pk_fma_f32 v[38:39], v[110:111], v[38:39], v[114:115]
	v_pk_fma_f32 v[36:37], v[108:109], v[36:37], v[112:113]
	v_pk_fma_f32 v[6:7], v[62:63], v[6:7], v[38:39]
	v_pk_fma_f32 v[4:5], v[60:61], v[4:5], v[36:37]
	v_pk_fma_f32 v[2:3], v[58:59], v[2:3], v[6:7]
	v_pk_fma_f32 v[0:1], v[56:57], v[0:1], v[4:5]
	s_nop 0
	v_mov_b64_e32 v[4:5], v[16:17]
	v_mov_b64_e32 v[6:7], v[18:19]
	s_nop 1
	v_mov_b32_dpp v36, v4 row_ror:1 row_mask:0xf bank_mask:0xf bound_ctrl:1
	v_mov_b32_dpp v4, v4 row_ror:2 row_mask:0xf bank_mask:0xf bound_ctrl:1
	v_mov_b32_dpp v37, v5 row_ror:1 row_mask:0xf bank_mask:0xf bound_ctrl:1
	v_mov_b32_dpp v5, v5 row_ror:2 row_mask:0xf bank_mask:0xf bound_ctrl:1
	v_mov_b32_dpp v38, v6 row_ror:1 row_mask:0xf bank_mask:0xf bound_ctrl:1
	v_mov_b32_dpp v6, v6 row_ror:2 row_mask:0xf bank_mask:0xf bound_ctrl:1
	v_mov_b32_dpp v39, v7 row_ror:1 row_mask:0xf bank_mask:0xf bound_ctrl:1
	v_mov_b32_dpp v7, v7 row_ror:2 row_mask:0xf bank_mask:0xf bound_ctrl:1
	v_mov_b32_dpp v36, v28 row_shr:1 row_mask:0xf bank_mask:0xf
	v_mov_b32_dpp v4, v28 row_shr:2 row_mask:0xf bank_mask:0xf
	v_mov_b32_dpp v37, v29 row_shr:1 row_mask:0xf bank_mask:0xf
	v_mov_b32_dpp v5, v29 row_shr:2 row_mask:0xf bank_mask:0xf
	v_mov_b32_dpp v38, v30 row_shr:1 row_mask:0xf bank_mask:0xf
	v_mov_b32_dpp v6, v30 row_shr:2 row_mask:0xf bank_mask:0xf
	v_mov_b32_dpp v39, v31 row_shr:1 row_mask:0xf bank_mask:0xf
	v_mov_b32_dpp v7, v31 row_shr:2 row_mask:0xf bank_mask:0xf
	v_pk_fma_f32 v[30:31], v[110:111], v[30:31], v[114:115]
	v_pk_fma_f32 v[28:29], v[108:109], v[28:29], v[112:113]
	v_pk_fma_f32 v[30:31], v[62:63], v[38:39], v[30:31]
	v_pk_fma_f32 v[28:29], v[60:61], v[36:37], v[28:29]
	v_pk_fma_f32 v[6:7], v[58:59], v[6:7], v[30:31]
	v_pk_fma_f32 v[4:5], v[56:57], v[4:5], v[28:29]
	s_nop 0
	v_mov_b64_e32 v[30:31], v[10:11]
	v_mov_b64_e32 v[28:29], v[8:9]
	s_nop 1
	v_mov_b32_dpp v36, v28 row_ror:1 row_mask:0xf bank_mask:0xf bound_ctrl:1
	v_mov_b32_dpp v28, v28 row_ror:2 row_mask:0xf bank_mask:0xf bound_ctrl:1
	v_mov_b32_dpp v37, v29 row_ror:1 row_mask:0xf bank_mask:0xf bound_ctrl:1
	v_mov_b32_dpp v29, v29 row_ror:2 row_mask:0xf bank_mask:0xf bound_ctrl:1
	v_mov_b32_dpp v38, v30 row_ror:1 row_mask:0xf bank_mask:0xf bound_ctrl:1
	v_mov_b32_dpp v30, v30 row_ror:2 row_mask:0xf bank_mask:0xf bound_ctrl:1
	v_mov_b32_dpp v39, v31 row_ror:1 row_mask:0xf bank_mask:0xf bound_ctrl:1
	v_mov_b32_dpp v31, v31 row_ror:2 row_mask:0xf bank_mask:0xf bound_ctrl:1
	v_mov_b32_dpp v36, v16 row_shr:1 row_mask:0xf bank_mask:0xf
	v_mov_b32_dpp v28, v16 row_shr:2 row_mask:0xf bank_mask:0xf
	v_mov_b32_dpp v37, v17 row_shr:1 row_mask:0xf bank_mask:0xf
	v_mov_b32_dpp v29, v17 row_shr:2 row_mask:0xf bank_mask:0xf
	v_mov_b32_dpp v38, v18 row_shr:1 row_mask:0xf bank_mask:0xf
	v_mov_b32_dpp v30, v18 row_shr:2 row_mask:0xf bank_mask:0xf
	v_mov_b32_dpp v39, v19 row_shr:1 row_mask:0xf bank_mask:0xf
	v_mov_b32_dpp v31, v19 row_shr:2 row_mask:0xf bank_mask:0xf
	v_pk_fma_f32 v[18:19], v[110:111], v[18:19], v[114:115]
	v_pk_fma_f32 v[16:17], v[108:109], v[16:17], v[112:113]
	v_pk_fma_f32 v[18:19], v[62:63], v[38:39], v[18:19]
	v_pk_fma_f32 v[16:17], v[60:61], v[36:37], v[16:17]
	v_pk_fma_f32 v[18:19], v[58:59], v[30:31], v[18:19]
	v_pk_fma_f32 v[16:17], v[56:57], v[28:29], v[16:17]
	s_nop 0
	s_waitcnt lgkmcnt(0)
	s_nop 1
	v_mov_b32_dpp v28, v120 row_ror:1 row_mask:0xf bank_mask:0xf bound_ctrl:1
	v_mov_b32_dpp v30, v120 row_ror:2 row_mask:0xf bank_mask:0xf bound_ctrl:1
	v_mov_b32_dpp v29, v121 row_ror:1 row_mask:0xf bank_mask:0xf bound_ctrl:1
	v_mov_b32_dpp v31, v121 row_ror:2 row_mask:0xf bank_mask:0xf bound_ctrl:1
	v_mov_b32_dpp v36, v122 row_ror:1 row_mask:0xf bank_mask:0xf bound_ctrl:1
	v_mov_b32_dpp v38, v122 row_ror:2 row_mask:0xf bank_mask:0xf bound_ctrl:1
	v_mov_b32_dpp v37, v123 row_ror:1 row_mask:0xf bank_mask:0xf bound_ctrl:1
	v_mov_b32_dpp v39, v123 row_ror:2 row_mask:0xf bank_mask:0xf bound_ctrl:1
	v_mov_b32_dpp v28, v8 row_shr:1 row_mask:0xf bank_mask:0xf
	v_mov_b32_dpp v30, v8 row_shr:2 row_mask:0xf bank_mask:0xf
	v_mov_b32_dpp v29, v9 row_shr:1 row_mask:0xf bank_mask:0xf
	v_mov_b32_dpp v31, v9 row_shr:2 row_mask:0xf bank_mask:0xf
	v_mov_b32_dpp v36, v10 row_shr:1 row_mask:0xf bank_mask:0xf
	v_mov_b32_dpp v38, v10 row_shr:2 row_mask:0xf bank_mask:0xf
	v_mov_b32_dpp v37, v11 row_shr:1 row_mask:0xf bank_mask:0xf
	v_mov_b32_dpp v39, v11 row_shr:2 row_mask:0xf bank_mask:0xf
	v_pk_fma_f32 v[10:11], v[110:111], v[10:11], v[114:115]
	v_pk_fma_f32 v[8:9], v[108:109], v[8:9], v[112:113]
	v_pk_fma_f32 v[10:11], v[62:63], v[36:37], v[10:11]
	v_pk_fma_f32 v[8:9], v[60:61], v[28:29], v[8:9]
	v_pk_fma_f32 v[38:39], v[58:59], v[38:39], v[10:11]
	v_pk_fma_f32 v[36:37], v[56:57], v[30:31], v[8:9]
	s_nop 0
	v_mul_f32_e32 v8, v100, v100
	v_mul_f32_e32 v9, v101, v101
	v_mul_f32_e32 v10, v102, v102
	v_mul_f32_e32 v11, v103, v103
	v_fmamk_f32 v8, v8, 0xbdd2d3e2, v215
	v_fmamk_f32 v9, v9, 0xbdd2d3e2, v215
	v_fmamk_f32 v10, v10, 0xbdd2d3e2, v215
	v_fmamk_f32 v11, v11, 0xbdd2d3e2, v215
	v_mul_f32_e32 v8, v100, v8
	v_mul_f32_e32 v9, v101, v9
	v_mul_f32_e32 v10, v102, v10
	v_mul_f32_e32 v11, v103, v11
	v_exp_f32_e32 v8, v8
	v_exp_f32_e32 v9, v9
	v_exp_f32_e32 v10, v10
	v_exp_f32_e32 v11, v11
	v_add_f32_e32 v8, 1.0, v8
	v_add_f32_e32 v9, 1.0, v9
	v_add_f32_e32 v10, 1.0, v10
	v_add_f32_e32 v11, 1.0, v11
	v_rcp_f32_e32 v8, v8
	v_rcp_f32_e32 v9, v9
	v_rcp_f32_e32 v10, v10
	v_rcp_f32_e32 v11, v11
	v_pk_mul_f32 v[8:9], v[100:101], v[8:9]
	s_nop 0
	v_pk_mul_f32 v[8:9], v[8:9], v[104:105]
	v_pk_mul_f32 v[10:11], v[102:103], v[10:11]
	s_nop 0
	v_pk_mul_f32 v[10:11], v[10:11], v[106:107]
	s_nop 0
	v_mul_f32_e32 v28, v96, v96
	v_mul_f32_e32 v29, v97, v97
	v_mul_f32_e32 v30, v98, v98
	v_mul_f32_e32 v31, v99, v99
	v_fmamk_f32 v28, v28, 0xbdd2d3e2, v215
	v_fmamk_f32 v29, v29, 0xbdd2d3e2, v215
	v_fmamk_f32 v30, v30, 0xbdd2d3e2, v215
	v_fmamk_f32 v31, v31, 0xbdd2d3e2, v215
	v_mul_f32_e32 v28, v96, v28
	v_mul_f32_e32 v29, v97, v29
	v_mul_f32_e32 v30, v98, v30
	v_mul_f32_e32 v31, v99, v31
	v_exp_f32_e32 v28, v28
	v_exp_f32_e32 v29, v29
	v_exp_f32_e32 v30, v30
	v_exp_f32_e32 v31, v31
	v_add_f32_e32 v28, 1.0, v28
	v_add_f32_e32 v29, 1.0, v29
	v_add_f32_e32 v30, 1.0, v30
	v_add_f32_e32 v31, 1.0, v31
	v_rcp_f32_e32 v28, v28
	v_rcp_f32_e32 v29, v29
	v_rcp_f32_e32 v30, v30
	v_rcp_f32_e32 v31, v31
	v_pk_mul_f32 v[28:29], v[96:97], v[28:29]
	s_nop 0
	v_pk_mul_f32 v[28:29], v[28:29], v[116:117]
	v_pk_mul_f32 v[30:31], v[98:99], v[30:31]
	s_nop 0
	v_pk_mul_f32 v[30:31], v[30:31], v[118:119]
	s_nop 0
	v_mul_f32_e32 v56, v44, v44
	v_mul_f32_e32 v57, v45, v45
	v_mul_f32_e32 v58, v46, v46
	v_mul_f32_e32 v59, v47, v47
	v_fmamk_f32 v56, v56, 0xbdd2d3e2, v215
	v_fmamk_f32 v57, v57, 0xbdd2d3e2, v215
	v_fmamk_f32 v58, v58, 0xbdd2d3e2, v215
	v_fmamk_f32 v59, v59, 0xbdd2d3e2, v215
	v_mul_f32_e32 v56, v44, v56
	v_mul_f32_e32 v57, v45, v57
	v_mul_f32_e32 v58, v46, v58
	v_mul_f32_e32 v59, v47, v59
	v_exp_f32_e32 v56, v56
	v_exp_f32_e32 v57, v57
	v_exp_f32_e32 v58, v58
	v_exp_f32_e32 v59, v59
	v_add_f32_e32 v56, 1.0, v56
	v_add_f32_e32 v57, 1.0, v57
	v_add_f32_e32 v58, 1.0, v58
	v_add_f32_e32 v59, 1.0, v59
	v_rcp_f32_e32 v56, v56
	v_rcp_f32_e32 v57, v57
	v_rcp_f32_e32 v58, v58
	v_rcp_f32_e32 v59, v59
	v_pk_mul_f32 v[44:45], v[44:45], v[56:57]
	s_nop 0
	v_pk_mul_f32 v[12:13], v[44:45], v[12:13]
	v_pk_mul_f32 v[46:47], v[46:47], v[58:59]
	s_nop 0
	v_pk_mul_f32 v[14:15], v[46:47], v[14:15]
	s_nop 0
	v_mul_f32_e32 v44, v52, v52
	v_mul_f32_e32 v45, v53, v53
	v_mul_f32_e32 v46, v54, v54
	v_mul_f32_e32 v47, v55, v55
	v_fmamk_f32 v44, v44, 0xbdd2d3e2, v215
	v_fmamk_f32 v45, v45, 0xbdd2d3e2, v215
	v_fmamk_f32 v46, v46, 0xbdd2d3e2, v215
	v_fmamk_f32 v47, v47, 0xbdd2d3e2, v215
	v_mul_f32_e32 v44, v52, v44
	v_mul_f32_e32 v45, v53, v45
	v_mul_f32_e32 v46, v54, v46
	v_mul_f32_e32 v47, v55, v47
	v_exp_f32_e32 v44, v44
	v_exp_f32_e32 v45, v45
	v_exp_f32_e32 v46, v46
	v_exp_f32_e32 v47, v47
	v_add_f32_e32 v44, 1.0, v44
	v_add_f32_e32 v45, 1.0, v45
	v_add_f32_e32 v46, 1.0, v46
	v_add_f32_e32 v47, 1.0, v47
	v_rcp_f32_e32 v44, v44
	v_rcp_f32_e32 v45, v45
	v_rcp_f32_e32 v46, v46
	v_rcp_f32_e32 v47, v47
	v_pk_mul_f32 v[44:45], v[52:53], v[44:45]
	s_nop 0
	v_pk_mul_f32 v[20:21], v[44:45], v[20:21]
	v_pk_mul_f32 v[46:47], v[54:55], v[46:47]
	s_nop 0
	v_pk_mul_f32 v[22:23], v[46:47], v[22:23]
	s_nop 0
	v_mul_f32_e32 v44, v40, v40
	v_mul_f32_e32 v45, v41, v41
	v_mul_f32_e32 v46, v42, v42
	v_mul_f32_e32 v47, v43, v43
	v_fmamk_f32 v44, v44, 0xbdd2d3e2, v215
	v_fmamk_f32 v45, v45, 0xbdd2d3e2, v215
	v_fmamk_f32 v46, v46, 0xbdd2d3e2, v215
	v_fmamk_f32 v47, v47, 0xbdd2d3e2, v215
	v_mul_f32_e32 v44, v40, v44
	v_mul_f32_e32 v45, v41, v45
	v_mul_f32_e32 v46, v42, v46
	v_mul_f32_e32 v47, v43, v47
	v_exp_f32_e32 v44, v44
	v_exp_f32_e32 v45, v45
	v_exp_f32_e32 v46, v46
	v_exp_f32_e32 v47, v47
	v_add_f32_e32 v44, 1.0, v44
	v_add_f32_e32 v45, 1.0, v45
	v_add_f32_e32 v46, 1.0, v46
	v_add_f32_e32 v47, 1.0, v47
	v_rcp_f32_e32 v44, v44
	v_rcp_f32_e32 v45, v45
	v_rcp_f32_e32 v46, v46
	v_rcp_f32_e32 v47, v47
	v_pk_mul_f32 v[40:41], v[40:41], v[44:45]
	s_nop 0
	v_pk_mul_f32 v[36:37], v[40:41], v[36:37]
	v_pk_mul_f32 v[42:43], v[42:43], v[46:47]
	s_nop 0
	v_pk_mul_f32 v[38:39], v[42:43], v[38:39]
	s_nop 0
	v_mul_f32_e32 v40, v48, v48
	v_mul_f32_e32 v41, v49, v49
	v_mul_f32_e32 v42, v50, v50
	v_mul_f32_e32 v43, v51, v51
	v_fmamk_f32 v40, v40, 0xbdd2d3e2, v215
	v_fmamk_f32 v41, v41, 0xbdd2d3e2, v215
	v_fmamk_f32 v42, v42, 0xbdd2d3e2, v215
	v_fmamk_f32 v43, v43, 0xbdd2d3e2, v215
	v_mul_f32_e32 v40, v48, v40
	v_mul_f32_e32 v41, v49, v41
	v_mul_f32_e32 v42, v50, v42
	v_mul_f32_e32 v43, v51, v43
	v_exp_f32_e32 v40, v40
	v_exp_f32_e32 v41, v41
	v_exp_f32_e32 v42, v42
	v_exp_f32_e32 v43, v43
	v_add_f32_e32 v40, 1.0, v40
	v_add_f32_e32 v41, 1.0, v41
	v_add_f32_e32 v42, 1.0, v42
	v_add_f32_e32 v43, 1.0, v43
	v_rcp_f32_e32 v40, v40
	v_rcp_f32_e32 v41, v41
	v_rcp_f32_e32 v42, v42
	v_rcp_f32_e32 v43, v43
	v_pk_mul_f32 v[40:41], v[48:49], v[40:41]
	s_nop 0
	v_pk_mul_f32 v[16:17], v[40:41], v[16:17]
	v_pk_mul_f32 v[42:43], v[50:51], v[42:43]
	s_nop 0
	v_pk_mul_f32 v[18:19], v[42:43], v[18:19]
	s_nop 0
	v_mul_f32_e32 v40, v32, v32
	v_mul_f32_e32 v41, v33, v33
	v_mul_f32_e32 v42, v34, v34
	v_mul_f32_e32 v43, v35, v35
	v_fmamk_f32 v40, v40, 0xbdd2d3e2, v215
	v_fmamk_f32 v41, v41, 0xbdd2d3e2, v215
	v_fmamk_f32 v42, v42, 0xbdd2d3e2, v215
	v_fmamk_f32 v43, v43, 0xbdd2d3e2, v215
	v_mul_f32_e32 v40, v32, v40
	v_mul_f32_e32 v41, v33, v41
	v_mul_f32_e32 v42, v34, v42
	v_mul_f32_e32 v43, v35, v43
	v_exp_f32_e32 v40, v40
	v_exp_f32_e32 v41, v41
	v_exp_f32_e32 v42, v42
	v_exp_f32_e32 v43, v43
	v_add_f32_e32 v40, 1.0, v40
	v_add_f32_e32 v41, 1.0, v41
	v_add_f32_e32 v42, 1.0, v42
	v_add_f32_e32 v43, 1.0, v43
	v_rcp_f32_e32 v40, v40
	v_rcp_f32_e32 v41, v41
	v_rcp_f32_e32 v42, v42
	v_rcp_f32_e32 v43, v43
	v_pk_mul_f32 v[32:33], v[32:33], v[40:41]
	s_nop 0
	v_pk_mul_f32 v[4:5], v[32:33], v[4:5]
	v_pk_mul_f32 v[34:35], v[34:35], v[42:43]
	s_nop 0
	v_pk_mul_f32 v[6:7], v[34:35], v[6:7]
	s_nop 0
	v_mul_f32_e32 v32, v24, v24
	v_mul_f32_e32 v33, v25, v25
	v_mul_f32_e32 v34, v26, v26
	v_mul_f32_e32 v35, v27, v27
	v_fmamk_f32 v32, v32, 0xbdd2d3e2, v215
	v_fmamk_f32 v33, v33, 0xbdd2d3e2, v215
	v_fmamk_f32 v34, v34, 0xbdd2d3e2, v215
	v_fmamk_f32 v35, v35, 0xbdd2d3e2, v215
	v_mul_f32_e32 v32, v24, v32
	v_mul_f32_e32 v33, v25, v33
	v_mul_f32_e32 v34, v26, v34
	v_mul_f32_e32 v35, v27, v35
	v_exp_f32_e32 v32, v32
	v_exp_f32_e32 v33, v33
	v_exp_f32_e32 v34, v34
	v_exp_f32_e32 v35, v35
	v_add_f32_e32 v32, 1.0, v32
	v_add_f32_e32 v33, 1.0, v33
	v_add_f32_e32 v34, 1.0, v34
	v_add_f32_e32 v35, 1.0, v35
	v_rcp_f32_e32 v32, v32
	v_rcp_f32_e32 v33, v33
	v_rcp_f32_e32 v34, v34
	v_rcp_f32_e32 v35, v35
	v_pk_mul_f32 v[24:25], v[24:25], v[32:33]
	s_nop 0
	v_pk_mul_f32 v[0:1], v[24:25], v[0:1]
	v_pk_mul_f32 v[26:27], v[26:27], v[34:35]
	s_nop 0
	v_pk_mul_f32 v[2:3], v[26:27], v[2:3]
	s_nop 0
	s_ashr_i32 s61, s60, 31
	s_ashr_i32 s29, s28, 31
	s_and_saveexec_b64 s[8:9], s[2:3]
	s_cbranch_execz .LBB0_999
	v_cvt_pk_bf16_f32 v26, v8, v9
	v_cvt_pk_bf16_f32 v27, v10, v11
	v_lshl_add_u64 v[8:9], s[60:61], 0, v[178:179]
	v_mov_b64_e32 v[10:11], s[18:19]
	v_mad_u64_u32 v[10:11], s[14:15], v8, s89, v[10:11]
	v_mad_i32_i24 v11, v9, s89, v11
	v_lshl_add_u64 v[8:9], s[28:29], 1, v[10:11]
	v_cvt_pk_bf16_f32 v24, v64, v65
	v_cvt_pk_bf16_f32 v25, v66, v67
	v_lshl_add_u64 v[8:9], v[8:9], 0, v[172:173]
	global_store_dwordx4 v[8:9], v[24:27], off nt
